# attention: the lane-32 step of the cross-lane max / sum uses v_permlane32_swap instead of an LDS bpermute round trip
# speedup vs baseline: 1.0047x; 1.0000x over previous
; DI int otid() { int t = threadIdx.x & 255; asm volatile("" : "+v"(t)); return t; }
; template <int NKB>
; DI void attn_unit(const Params& p, int l, int mode, int grp, int head, int r0, int dil, int i0, int sub_len, int W, h16* lds) {
;   unsigned char* ws = p.ws;
;   const h16* P = (const h16*)(ws + OFF_PS);
;   h16* Qi = lds; h16* Ki = lds + 64 * LDH; h16* Vt = lds + 128 * LDH; h16* Pi = lds + 192 * LDH;
;   const int tid = otid(), lane = tid & 63, w = tid >> 6, r = lane & 15, q = lane >> 4;
;   const int lrow = tid >> 2, seg = tid & 3;
;   int qcol, kcol, vcol;
;   if (mode == 0) { qcol = 1024 + grp * 256 + head * 64; kcol = 1792 + grp * 256 + head * 64; vcol = 2560 + grp * 256 + head * 64; }
;   else { qcol = 4352 + head * 64; kcol = 4864 + (head >> 2) * 64; vcol = 4992 + (head >> 2) * 64; }
;   __syncthreads();
;   {
;     const size_t pos = (size_t)r0 + (size_t)dil * (i0 + lrow);
;     const h16* g = P + pos * NSM + qcol + 16 * seg;
;     img_store_nat(Qi, lrow, seg, *(const u4v*)g, *(const u4v*)(g + 8));
;   }
;   float mrow[4], lsum[4];
;   f4v O[4];
;   float m_init = -1e30f, l_init = 0.f;
;   if (mode == 1) { m_init = p.d_sink[l * 8 + head]; l_init = 1.f; }
; #pragma unroll
;   for (int i = 0; i < 4; ++i) { mrow[i] = m_init; lsum[i] = l_init; O[i] = (f4v){0.f, 0.f, 0.f, 0.f}; }
;   u4v pk0, pk1, pv0, pv1;
;     ...
;   ATT_PREFETCH(0);
; DI void phase_m2(const Params& p, int l, int bid, int nb, h16* lds) {
;     ...
;   for (int u = ustart; u < total; u += ustep) {
;     int v = u;
;     if (v >= 5288) { v -= 5288; if (v < nA) conv_one(p, l, 2560 + v, lds); else conv_one(p, l + 1, v - nA, lds); continue; }
;     if (v < 32) { dn_c2_unit(p, v >> 2, v & 3); continue; }
;     if ((v -= 32) < 136) { mlstm_a2_unit(p, v); continue; }
;     if ((v -= 136) < 2048) { attn_unit<5>(p, l, 1, 0, v & 7, 0, 1, (v >> 3) * 64, SEQ, 128, lds); continue; }
;     v -= 2048;
;     const int grp = v >> 10, x = v & 1023, head = x & 3, tl = x >> 2;
;     const int dil = (grp == 0) ? 1 : (grp == 1) ? 4 : 16;
;     const int sub = SEQ / dil, tps = sub >> 6;
;     const int res = tl / tps, ti = tl % tps;
;     attn_unit<3>(p, l, 0, grp, head, res, dil, ti * 64, sub, 64, lds);
.LBB0_897:
	s_movk_i32 s2, 0x14a8
	v_cmp_gt_i32_e32 vcc, s2, v1
	s_and_saveexec_b64 s[2:3], vcc
	s_xor_b64 s[84:85], exec, s[2:3]
	s_cbranch_execz .LBB0_960
	v_cmp_lt_i32_e32 vcc, 31, v1
	s_and_saveexec_b64 s[2:3], vcc
	s_xor_b64 s[86:87], exec, s[2:3]
	s_cbranch_execz .LBB0_953
	s_movk_i32 s2, 0xa7
	v_cmp_lt_u32_e32 vcc, s2, v1
	s_and_saveexec_b64 s[2:3], vcc
	s_xor_b64 s[88:89], exec, s[2:3]
	s_cbranch_execz .LBB0_915
	s_movk_i32 s2, 0x8a7
	v_cmp_lt_u32_e32 vcc, s2, v1
	s_and_saveexec_b64 s[2:3], vcc
	s_xor_b64 s[34:35], exec, s[2:3]
	s_cbranch_execz .LBB0_910
	v_readfirstlane_b32 s36, v1
	v_readfirstlane_b32 s58, v182
	s_lshr_b32 s58, s58, 6
	s_sub_u32 s51, s36, 0x8a8
	s_and_b32 s56, s51, 15
	s_sub_u32 s56, s56, 8
	s_and_b32 s56, s56, 15
	s_lshr_b32 s56, s56, 1
	s_lshr_b32 s57, s51, 4
	s_lshl_b32 s57, s57, 1
	s_and_b32 s59, s51, 1
	s_or_b32 s57, s57, s59
	s_mul_i32 s59, s57, 0xaaab
	s_lshr_b32 s59, s59, 19
	s_mul_i32 s62, s59, 12
	s_sub_u32 s62, s57, s62
	s_lshr_b32 s61, s62, 2
	s_and_b32 s37, s62, 3
	s_lshl_b32 s62, s56, 5
	s_add_u32 s62, s62, s59
	s_lshl_b32 s63, s61, 1
	s_lshl_b32 s60, 1, s63
	s_movk_i32 s39, 0x2800
	s_lshl_b32 s39, s39, s63
	s_movk_i32 s41, 0x4000
	s_lshr_b32 s41, s41, s63
	s_sub_u32 s51, 8, s63
	s_lshr_b32 s40, s62, s51
	s_movk_i32 s51, 0x100
	s_lshr_b32 s51, s51, s63
	s_sub_u32 s51, s51, 1
	s_and_b32 s38, s62, s51
	s_lshl_b32 s38, s38, 6
	s_lshl_b32 s51, s61, 9
	s_lshl_b32 s56, s37, 7
	s_add_u32 s51, s51, s56
	s_add_u32 s53, s51, 0x800
	s_add_u32 s54, s51, 0xe00
	s_add_u32 s55, s51, 0x1400
	v_and_b32_e32 v179, 63, v182
	v_and_b32_e32 v200, 15, v179
	v_lshrrev_b32_e32 v201, 4, v179
	v_lshlrev_b32_e32 v202, 4, v201
	v_mad_u32_u24 v2, v200, s39, v202
	v_add_u32_e32 v203, 16, v200
	v_mad_u32_u24 v3, v203, s39, v202
	v_add_u32_e32 v203, 32, v200
	v_mad_u32_u24 v4, v203, s39, v202
	v_add_u32_e32 v203, 48, v200
	v_mad_u32_u24 v5, v203, s39, v202
	s_lshl_b32 s51, s58, 4
	v_add_u32_e32 v203, s51, v200
	v_mad_u32_u24 v248, v203, s39, v202
	v_lshlrev_b32_e32 v160, 2, v201
	v_sub_u32_e32 v160, v160, v203
	s_lshl_b32 s51, s60, 9
	v_mul_u32_u24_e32 v249, s51, v203
	s_lshl_b32 s51, s60, 5
	v_mul_u32_u24_e32 v203, s51, v203
	v_lshl_add_u32 v249, v201, 3, v249
	v_lshrrev_b32_e32 v203, 3, v179
	s_lshl_b32 s51, s58, 4
	v_add_u32_e32 v203, s51, v203
	v_and_b32_e32 v202, 7, v179
	v_lshlrev_b32_e32 v202, 4, v202
	v_mad_u32_u24 v6, v203, s39, v202
	v_add_u32_e32 v200, 8, v203
	v_mad_u32_u24 v7, v200, s39, v202
	s_movk_i32 s57, 0x90
	v_mad_u32_u24 v158, v203, s57, v183
	v_add_u32_e32 v158, v158, v202
	v_and_b32_e32 v200, 15, v179
	v_mad_u32_u24 v8, v200, s57, v183
	v_lshl_add_u32 v8, v201, 4, v8
	v_lshrrev_b32_e32 v203, 2, v179
	v_mad_u32_u24 v159, v203, s57, v183
	v_and_b32_e32 v203, 3, v179
	v_lshl_add_u32 v159, v203, 3, v159
	v_add_u32_e32 v159, 0x2400, v159
	v_xor_b32_e32 v174, 16, v179
	v_lshlrev_b32_e32 v174, 2, v174
	v_xor_b32_e32 v175, 32, v179
	v_lshlrev_b32_e32 v175, 2, v175
	s_mul_i32 s51, s60, s38
	s_add_u32 s51, s51, s40
	s_mul_i32 s56, s51, 0x2800
	s_add_u32 s56, s56, s53
	s_add_u32 s42, s0, s56
	s_addc_u32 s43, s1, 0
	global_load_dwordx4 v[10:13], v248, s[42:43]
	global_load_dwordx4 v[14:17], v248, s[42:43] offset:64
	v_readlane_b32 s48, v254, 32
	v_readlane_b32 s49, v254, 33
	v_readlane_b32 s16, v254, 34
	v_readlane_b32 s17, v254, 35
	s_lshl_b32 s56, s61, 14
	s_add_u32 s56, s56, s51
	s_lshl_b32 s57, s56, 9
	s_lshl_b32 s59, s37, 7
	s_add_u32 s57, s57, s59
	s_add_u32 s48, s48, s57
	s_addc_u32 s49, s49, 0
	s_lshl_b32 s57, s56, 5
	s_lshl_b32 s59, s37, 3
	s_add_u32 s57, s57, s59
	s_add_u32 s16, s16, s57
	s_addc_u32 s17, s17, 0
	v_mov_b32_e32 v176, 0xf149f2ca
	v_mov_b32_e32 v177, 0
	v_mov_b32_e32 v138, 0
	v_mov_b32_e32 v139, 0
	v_mov_b32_e32 v140, 0
	v_mov_b32_e32 v141, 0
	v_mov_b32_e32 v142, 0
	v_mov_b32_e32 v143, 0
	v_mov_b32_e32 v144, 0
	v_mov_b32_e32 v145, 0
	v_mov_b32_e32 v146, 0
	v_mov_b32_e32 v147, 0
	v_mov_b32_e32 v148, 0
	v_mov_b32_e32 v149, 0
	v_mov_b32_e32 v150, 0
	v_mov_b32_e32 v151, 0
	v_mov_b32_e32 v152, 0
	v_mov_b32_e32 v153, 0
	s_sub_u32 s50, s38, 64
	s_cmp_ge_i32 s50, 0
	s_cselect_b32 s56, 1, 0
	s_cmp_lt_i32 s50, s41
	s_cselect_b32 s57, 1, 0
	s_and_b32 s2, s56, s57
	s_cmp_eq_u32 s2, 1
	s_cselect_b32 s50, s50, s38
	s_mul_i32 s50, s50, s60
	s_add_u32 s50, s50, s40
	s_mul_i32 s50, s50, 0x2800
	s_add_u32 s56, s50, s54
	s_add_u32 s44, s0, s56
	s_addc_u32 s45, s1, 0
	s_add_u32 s56, s50, s55
	s_add_u32 s46, s0, s56
	s_addc_u32 s47, s1, 0
	global_load_dwordx4 v[50:53], v6, s[44:45]
	global_load_dwordx4 v[54:57], v7, s[44:45]
	global_load_dwordx4 v[58:61], v6, s[46:47]
	global_load_dwordx4 v[62:65], v7, s[46:47]
	s_add_u32 s50, s38, 0
	s_cmp_ge_i32 s50, 0
	s_cselect_b32 s56, 1, 0
	s_cmp_lt_i32 s50, s41
	s_cselect_b32 s57, 1, 0
	s_and_b32 s3, s56, s57
	s_cmp_eq_u32 s3, 1
	s_cselect_b32 s50, s50, s38
	s_mul_i32 s50, s50, s60
	s_add_u32 s50, s50, s40
	s_mul_i32 s50, s50, 0x2800
	s_add_u32 s56, s50, s54
	s_add_u32 s44, s0, s56
	s_addc_u32 s45, s1, 0
	s_add_u32 s56, s50, s55
	s_add_u32 s46, s0, s56
	s_addc_u32 s47, s1, 0
	global_load_dwordx4 v[66:69], v6, s[44:45]
	global_load_dwordx4 v[70:73], v7, s[44:45]
	global_load_dwordx4 v[74:77], v6, s[46:47]
	global_load_dwordx4 v[78:81], v7, s[46:47]
	s_waitcnt vmcnt(4)
	ds_write_b128 v158, v[50:53] offset:0
	ds_write_b128 v158, v[54:57] offset:1152
	ds_write_b128 v158, v[58:61] offset:9216
	ds_write_b128 v158, v[62:65] offset:10368
	s_waitcnt lgkmcnt(0)
	s_barrier
; DI float grp16_max(float v) { v = fmaxf(v, __shfl_xor(v, 1)); v = fmaxf(v, __shfl_xor(v, 2)); v = fmaxf(v, __shfl_xor(v, 4)); v = fmaxf(v, __shfl_xor(v, 8)); return v; }
; template <int NKB>
; DI void attn_unit(const Params& p, int l, int mode, int grp, int head, int r0, int dil, int i0, int sub_len, int W, h16* lds) {
;     ...
;   for (int kb = 0; kb < NKB; ++kb) {
;     const int j0 = i0 - W + 64 * kb;
;     const bool inr = (j0 >= 0) && (j0 < sub_len);
;     __syncthreads();
;     img_store_nat(Ki, lrow, seg, pk0, pk1);
;     img_store_T(Vt, lrow, seg, pv0, pv1);
;     __syncthreads();
;     if (kb + 1 < NKB) ATT_PREFETCH(kb + 1);
;     f4v S[4];
; #pragma unroll
;     for (int i = 0; i < 4; ++i) S[i] = (f4v){0.f, 0.f, 0.f, 0.f};
;     mm64(Qi, Ki, S, w, lane);
;     float mx[4], al[4], rsum[4];
;     bool vm[4][4];
; #pragma unroll
;     for (int rg = 0; rg < 4; ++rg) {
;       const int row = 16 * w + 4 * q + rg;
;       float m_ = -1e30f;
; #pragma unroll
;       for (int nt = 0; nt < 4; ++nt) {
;         const int key = 16 * nt + r;
;         const int delta = row - key + W - 64 * kb;
;         const bool ok = inr && (delta >= -W) && (delta <= W);
;         vm[nt][rg] = ok;
;         float s = S[nt][rg] * 0.125f;
;         S[nt][rg] = s;
;         if (ok) m_ = fmaxf(m_, s);
;       }
;       mx[rg] = grp16_max(m_);
;     }
	s_add_u32 s50, s38, 64
	s_cmp_ge_i32 s50, 0
	s_cselect_b32 s56, 1, 0
	s_cmp_lt_i32 s50, s41
	s_cselect_b32 s57, 1, 0
	s_and_b32 s4, s56, s57
	s_cmp_eq_u32 s4, 1
	s_cselect_b32 s50, s50, s38
	s_mul_i32 s50, s50, s60
	s_add_u32 s50, s50, s40
	s_mul_i32 s50, s50, 0x2800
	s_add_u32 s56, s50, s54
	s_add_u32 s44, s0, s56
	s_addc_u32 s45, s1, 0
	s_add_u32 s56, s50, s55
	s_add_u32 s46, s0, s56
	s_addc_u32 s47, s1, 0
	global_load_dwordx4 v[50:53], v6, s[44:45]
	global_load_dwordx4 v[54:57], v7, s[44:45]
	global_load_dwordx4 v[58:61], v6, s[46:47]
	global_load_dwordx4 v[62:65], v7, s[46:47]
	s_cmp_eq_u32 s2, 1
	s_cbranch_scc0 .Lat0_kb0_end
	ds_read_b128 v[18:21], v8 offset:0
	ds_read_b128 v[22:25], v8 offset:64
	ds_read_b128 v[26:29], v8 offset:2304
	ds_read_b128 v[30:33], v8 offset:2368
	ds_read_b128 v[34:37], v8 offset:4608
	ds_read_b128 v[38:41], v8 offset:4672
	ds_read_b128 v[42:45], v8 offset:6912
	ds_read_b128 v[46:49], v8 offset:6976
	ds_read_b64_tr_b16 v[216:217], v159
	ds_read_b64_tr_b16 v[218:219], v159 offset:2304
	ds_read_b64_tr_b16 v[220:221], v159 offset:4608
	ds_read_b64_tr_b16 v[222:223], v159 offset:6912
	ds_read_b64_tr_b16 v[224:225], v159 offset:32
	ds_read_b64_tr_b16 v[226:227], v159 offset:2336
	ds_read_b64_tr_b16 v[228:229], v159 offset:4640
	ds_read_b64_tr_b16 v[230:231], v159 offset:6944
	ds_read_b64_tr_b16 v[232:233], v159 offset:64
	ds_read_b64_tr_b16 v[234:235], v159 offset:2368
	ds_read_b64_tr_b16 v[236:237], v159 offset:4672
	ds_read_b64_tr_b16 v[238:239], v159 offset:6976
	ds_read_b64_tr_b16 v[240:241], v159 offset:96
	ds_read_b64_tr_b16 v[242:243], v159 offset:2400
	ds_read_b64_tr_b16 v[244:245], v159 offset:4704
	ds_read_b64_tr_b16 v[246:247], v159 offset:7008
	s_waitcnt lgkmcnt(15)
	v_mfma_f32_16x16x32_f16 v[114:117], v[18:21], v[10:13], 0
	v_mfma_f32_16x16x32_f16 v[118:121], v[26:29], v[10:13], 0
	v_mfma_f32_16x16x32_f16 v[122:125], v[34:37], v[10:13], 0
	v_mfma_f32_16x16x32_f16 v[126:129], v[42:45], v[10:13], 0
	v_mfma_f32_16x16x32_f16 v[114:117], v[22:25], v[14:17], v[114:117]
	v_mfma_f32_16x16x32_f16 v[118:121], v[30:33], v[14:17], v[118:121]
	v_mfma_f32_16x16x32_f16 v[122:125], v[38:41], v[14:17], v[122:125]
	v_mfma_f32_16x16x32_f16 v[126:129], v[46:49], v[14:17], v[126:129]
	s_nop 7
	s_nop 7
	v_mul_f32_e32 v114, 0x3e000000, v114
	v_mul_f32_e32 v115, 0x3e000000, v115
	v_mul_f32_e32 v116, 0x3e000000, v116
	v_mul_f32_e32 v117, 0x3e000000, v117
	v_mul_f32_e32 v118, 0x3e000000, v118
	v_mul_f32_e32 v119, 0x3e000000, v119
	v_mul_f32_e32 v120, 0x3e000000, v120
	v_mul_f32_e32 v121, 0x3e000000, v121
	v_mul_f32_e32 v122, 0x3e000000, v122
	v_mul_f32_e32 v123, 0x3e000000, v123
	v_mul_f32_e32 v124, 0x3e000000, v124
	v_mul_f32_e32 v125, 0x3e000000, v125
	v_mul_f32_e32 v126, 0x3e000000, v126
	v_mul_f32_e32 v127, 0x3e000000, v127
	v_mul_f32_e32 v128, 0x3e000000, v128
	v_mul_f32_e32 v129, 0x3e000000, v129
	v_mov_b32_e32 v200, 0xf149f2ca
	v_cmp_le_i32_e32 vcc, 0, v160
	v_cndmask_b32_e32 v114, v200, v114, vcc
	v_cmp_le_i32_e32 vcc, -1, v160
	v_cndmask_b32_e32 v115, v200, v115, vcc
	v_cmp_le_i32_e32 vcc, -2, v160
	v_cndmask_b32_e32 v116, v200, v116, vcc
	v_cmp_le_i32_e32 vcc, -3, v160
	v_cndmask_b32_e32 v117, v200, v117, vcc
	v_cmp_le_i32_e32 vcc, -16, v160
	v_cndmask_b32_e32 v118, v200, v118, vcc
	v_cmp_le_i32_e32 vcc, -17, v160
	v_cndmask_b32_e32 v119, v200, v119, vcc
	v_cmp_le_i32_e32 vcc, -18, v160
	v_cndmask_b32_e32 v120, v200, v120, vcc
	v_cmp_le_i32_e32 vcc, -19, v160
	v_cndmask_b32_e32 v121, v200, v121, vcc
	v_cmp_le_i32_e32 vcc, -32, v160
	v_cndmask_b32_e32 v122, v200, v122, vcc
	v_cmp_le_i32_e32 vcc, -33, v160
	v_cndmask_b32_e32 v123, v200, v123, vcc
	v_cmp_le_i32_e32 vcc, -34, v160
	v_cndmask_b32_e32 v124, v200, v124, vcc
	v_cmp_le_i32_e32 vcc, -35, v160
	v_cndmask_b32_e32 v125, v200, v125, vcc
	v_cmp_le_i32_e32 vcc, -48, v160
	v_cndmask_b32_e32 v126, v200, v126, vcc
	v_cmp_le_i32_e32 vcc, -49, v160
	v_cndmask_b32_e32 v127, v200, v127, vcc
	v_cmp_le_i32_e32 vcc, -50, v160
	v_cndmask_b32_e32 v128, v200, v128, vcc
	v_cmp_le_i32_e32 vcc, -51, v160
	v_cndmask_b32_e32 v129, v200, v129, vcc
	v_max3_f32 v179, v114, v115, v116
	v_max3_f32 v179, v179, v117, v118
	v_max3_f32 v179, v179, v119, v120
	v_max3_f32 v179, v179, v121, v122
	v_max3_f32 v179, v179, v123, v124
	v_max3_f32 v179, v179, v125, v126
	v_max3_f32 v179, v179, v127, v128
	v_max_f32_e32 v179, v179, v129
	ds_bpermute_b32 v201, v174, v179
	s_waitcnt lgkmcnt(0)
; DI float grp16_sum(float v) { v += __shfl_xor(v, 1); v += __shfl_xor(v, 2); v += __shfl_xor(v, 4); v += __shfl_xor(v, 8); return v; }
; DI float grp16_max(float v) { v = fmaxf(v, __shfl_xor(v, 1)); v = fmaxf(v, __shfl_xor(v, 2)); v = fmaxf(v, __shfl_xor(v, 4)); v = fmaxf(v, __shfl_xor(v, 8)); return v; }
; template <int NKB>
; DI void attn_unit(const Params& p, int l, int mode, int grp, int head, int r0, int dil, int i0, int sub_len, int W, h16* lds) {
;     ...
;   for (int kb = 0; kb < NKB; ++kb) {
;     const int j0 = i0 - W + 64 * kb;
;     const bool inr = (j0 >= 0) && (j0 < sub_len);
;     __syncthreads();
;     img_store_nat(Ki, lrow, seg, pk0, pk1);
;     img_store_T(Vt, lrow, seg, pv0, pv1);
;     __syncthreads();
;     if (kb + 1 < NKB) ATT_PREFETCH(kb + 1);
;     f4v S[4];
; #pragma unroll
;     for (int i = 0; i < 4; ++i) S[i] = (f4v){0.f, 0.f, 0.f, 0.f};
;     mm64(Qi, Ki, S, w, lane);
;     float mx[4], al[4], rsum[4];
;     bool vm[4][4];
; #pragma unroll
;     for (int rg = 0; rg < 4; ++rg) {
;       const int row = 16 * w + 4 * q + rg;
;       float m_ = -1e30f;
; #pragma unroll
;       for (int nt = 0; nt < 4; ++nt) {
;         const int key = 16 * nt + r;
;         const int delta = row - key + W - 64 * kb;
;         const bool ok = inr && (delta >= -W) && (delta <= W);
;         vm[nt][rg] = ok;
;         float s = S[nt][rg] * 0.125f;
;         S[nt][rg] = s;
;         if (ok) m_ = fmaxf(m_, s);
;       }
;       mx[rg] = grp16_max(m_);
;     }
; #pragma unroll
;     for (int rg = 0; rg < 4; ++rg) {
;       const float mn = fmaxf(mrow[rg], mx[rg]);
;       al[rg] = __expf(mrow[rg] - mn);
;       mrow[rg] = mn;
;       float rs_ = 0.f;
; #pragma unroll
;       for (int nt = 0; nt < 4; ++nt) {
;         float pv = vm[nt][rg] ? __expf(S[nt][rg] - mn) : 0.f;
;         rs_ += pv;
;         Pi[(16 * w + 4 * q + rg) * LDH + 16 * nt + r] = (h16)pv;
;       }
;       rsum[rg] = grp16_sum(rs_);
;       lsum[rg] = lsum[rg] * al[rg] + rsum[rg];
;     }
; #pragma unroll
;     for (int et = 0; et < 4; ++et)
; #pragma unroll
;       for (int rg = 0; rg < 4; ++rg) O[et][rg] *= al[rg];
;     __syncthreads();
;     mm64(Pi, Vt, O, w, lane);
;   }
	v_max_f32_e32 v179, v179, v201
	v_mov_b32_e32 v201, v179
	s_nop 1
	v_permlane32_swap_b32 v201, v179
	s_nop 1
	v_max3_f32 v179, v179, v201, v176
	v_sub_f32_e32 v178, v176, v179
	v_mul_f32_e32 v178, 0x3fb8aa3b, v178
	v_exp_f32_e32 v178, v178
	v_mov_b32_e32 v176, v179
	v_mul_f32_e32 v202, 0xbfb8aa3b, v179
	v_mov_b32_e32 v203, 0x3fb8aa3b
	v_fma_f32 v114, v114, v203, v202
	v_fma_f32 v115, v115, v203, v202
	v_fma_f32 v116, v116, v203, v202
	v_fma_f32 v117, v117, v203, v202
	v_fma_f32 v118, v118, v203, v202
	v_fma_f32 v119, v119, v203, v202
	v_fma_f32 v120, v120, v203, v202
	v_fma_f32 v121, v121, v203, v202
	v_fma_f32 v122, v122, v203, v202
	v_fma_f32 v123, v123, v203, v202
	v_fma_f32 v124, v124, v203, v202
	v_fma_f32 v125, v125, v203, v202
	v_fma_f32 v126, v126, v203, v202
	v_fma_f32 v127, v127, v203, v202
	v_fma_f32 v128, v128, v203, v202
	v_fma_f32 v129, v129, v203, v202
	v_exp_f32_e32 v114, v114
	v_exp_f32_e32 v115, v115
	v_exp_f32_e32 v116, v116
	v_exp_f32_e32 v117, v117
	v_exp_f32_e32 v118, v118
	v_exp_f32_e32 v119, v119
	v_exp_f32_e32 v120, v120
	v_exp_f32_e32 v121, v121
	v_exp_f32_e32 v122, v122
	v_exp_f32_e32 v123, v123
	v_exp_f32_e32 v124, v124
	v_exp_f32_e32 v125, v125
	v_exp_f32_e32 v126, v126
	v_exp_f32_e32 v127, v127
	v_exp_f32_e32 v128, v128
	v_exp_f32_e32 v129, v129
	s_nop 0
	v_fma_f32 v177, v177, v178, v114
	v_add_f32_e32 v177, v177, v115
	v_add_f32_e32 v177, v177, v116
	v_add_f32_e32 v177, v177, v117
	v_add_f32_e32 v177, v177, v118
	v_add_f32_e32 v177, v177, v119
	v_add_f32_e32 v177, v177, v120
	v_add_f32_e32 v177, v177, v121
	v_add_f32_e32 v177, v177, v122
	v_add_f32_e32 v177, v177, v123
	v_add_f32_e32 v177, v177, v124
	v_add_f32_e32 v177, v177, v125
	v_add_f32_e32 v177, v177, v126
	v_add_f32_e32 v177, v177, v127
	v_add_f32_e32 v177, v177, v128
	v_add_f32_e32 v177, v177, v129
	v_cvt_pk_f16_f32 v130, v114, v115
	v_cvt_pk_f16_f32 v131, v116, v117
	v_cvt_pk_f16_f32 v132, v118, v119
	v_cvt_pk_f16_f32 v133, v120, v121
	v_cvt_pk_f16_f32 v134, v122, v123
	v_cvt_pk_f16_f32 v135, v124, v125
	v_cvt_pk_f16_f32 v136, v126, v127
	v_cvt_pk_f16_f32 v137, v128, v129
	v_pk_mul_f32 v[138:139], v[138:139], v[178:179] op_sel_hi:[1,0]
	v_pk_mul_f32 v[140:141], v[140:141], v[178:179] op_sel_hi:[1,0]
	v_pk_mul_f32 v[142:143], v[142:143], v[178:179] op_sel_hi:[1,0]
	v_pk_mul_f32 v[144:145], v[144:145], v[178:179] op_sel_hi:[1,0]
	v_pk_mul_f32 v[146:147], v[146:147], v[178:179] op_sel_hi:[1,0]
	v_pk_mul_f32 v[148:149], v[148:149], v[178:179] op_sel_hi:[1,0]
	v_pk_mul_f32 v[150:151], v[150:151], v[178:179] op_sel_hi:[1,0]
	v_pk_mul_f32 v[152:153], v[152:153], v[178:179] op_sel_hi:[1,0]
	s_nop 1
	v_mfma_f32_16x16x32_f16 v[138:141], v[216:219], v[130:133], v[138:141]
	v_mfma_f32_16x16x32_f16 v[142:145], v[224:227], v[130:133], v[142:145]
	v_mfma_f32_16x16x32_f16 v[146:149], v[232:235], v[130:133], v[146:149]
	v_mfma_f32_16x16x32_f16 v[150:153], v[240:243], v[130:133], v[150:153]
	v_mfma_f32_16x16x32_f16 v[138:141], v[220:223], v[134:137], v[138:141]
	v_mfma_f32_16x16x32_f16 v[142:145], v[228:231], v[134:137], v[142:145]
	v_mfma_f32_16x16x32_f16 v[146:149], v[236:239], v[134:137], v[146:149]
	v_mfma_f32_16x16x32_f16 v[150:153], v[244:247], v[134:137], v[150:153]
.Lat0_kb0_end:
	s_waitcnt vmcnt(4)
	ds_write_b128 v158, v[66:69] offset:18432
	ds_write_b128 v158, v[70:73] offset:19584
	ds_write_b128 v158, v[74:77] offset:27648
	ds_write_b128 v158, v[78:81] offset:28800
	s_waitcnt lgkmcnt(0)
	s_barrier
	s_cmp_eq_u32 s3, 1
	s_cbranch_scc0 .Lat0_kb1_end
	ds_read_b128 v[18:21], v8 offset:18432
	ds_read_b128 v[22:25], v8 offset:18496
	ds_read_b128 v[26:29], v8 offset:20736
	ds_read_b128 v[30:33], v8 offset:20800
	ds_read_b128 v[34:37], v8 offset:23040
	ds_read_b128 v[38:41], v8 offset:23104
	ds_read_b128 v[42:45], v8 offset:25344
	ds_read_b128 v[46:49], v8 offset:25408
	ds_read_b64_tr_b16 v[216:217], v159 offset:18432
	ds_read_b64_tr_b16 v[218:219], v159 offset:20736
	ds_read_b64_tr_b16 v[220:221], v159 offset:23040
	ds_read_b64_tr_b16 v[222:223], v159 offset:25344
	ds_read_b64_tr_b16 v[224:225], v159 offset:18464
	ds_read_b64_tr_b16 v[226:227], v159 offset:20768
	ds_read_b64_tr_b16 v[228:229], v159 offset:23072
	ds_read_b64_tr_b16 v[230:231], v159 offset:25376
	ds_read_b64_tr_b16 v[232:233], v159 offset:18496
	ds_read_b64_tr_b16 v[234:235], v159 offset:20800
	ds_read_b64_tr_b16 v[236:237], v159 offset:23104
	ds_read_b64_tr_b16 v[238:239], v159 offset:25408
	ds_read_b64_tr_b16 v[240:241], v159 offset:18528
	ds_read_b64_tr_b16 v[242:243], v159 offset:20832
	ds_read_b64_tr_b16 v[244:245], v159 offset:23136
	ds_read_b64_tr_b16 v[246:247], v159 offset:25440
	s_waitcnt lgkmcnt(15)
	v_mfma_f32_16x16x32_f16 v[114:117], v[18:21], v[10:13], 0
	v_mfma_f32_16x16x32_f16 v[118:121], v[26:29], v[10:13], 0
	v_mfma_f32_16x16x32_f16 v[122:125], v[34:37], v[10:13], 0
	v_mfma_f32_16x16x32_f16 v[126:129], v[42:45], v[10:13], 0
	v_mfma_f32_16x16x32_f16 v[114:117], v[22:25], v[14:17], v[114:117]
	v_mfma_f32_16x16x32_f16 v[118:121], v[30:33], v[14:17], v[118:121]
	v_mfma_f32_16x16x32_f16 v[122:125], v[38:41], v[14:17], v[122:125]
	v_mfma_f32_16x16x32_f16 v[126:129], v[46:49], v[14:17], v[126:129]
	s_nop 7
	s_nop 7
	v_mul_f32_e32 v114, 0x3e000000, v114
	v_mul_f32_e32 v115, 0x3e000000, v115
	v_mul_f32_e32 v116, 0x3e000000, v116
	v_mul_f32_e32 v117, 0x3e000000, v117
	v_mul_f32_e32 v118, 0x3e000000, v118
	v_mul_f32_e32 v119, 0x3e000000, v119
	v_mul_f32_e32 v120, 0x3e000000, v120
	v_mul_f32_e32 v121, 0x3e000000, v121
	v_mul_f32_e32 v122, 0x3e000000, v122
	v_mul_f32_e32 v123, 0x3e000000, v123
	v_mul_f32_e32 v124, 0x3e000000, v124
	v_mul_f32_e32 v125, 0x3e000000, v125
	v_mul_f32_e32 v126, 0x3e000000, v126
	v_mul_f32_e32 v127, 0x3e000000, v127
	v_mul_f32_e32 v128, 0x3e000000, v128
	v_mul_f32_e32 v129, 0x3e000000, v129
	v_max3_f32 v179, v114, v115, v116
	v_max3_f32 v179, v179, v117, v118
	v_max3_f32 v179, v179, v119, v120
	v_max3_f32 v179, v179, v121, v122
	v_max3_f32 v179, v179, v123, v124
	v_max3_f32 v179, v179, v125, v126
	v_max3_f32 v179, v179, v127, v128
	v_max_f32_e32 v179, v179, v129
	ds_bpermute_b32 v201, v174, v179
	s_waitcnt lgkmcnt(0)
; DI float grp16_sum(float v) { v += __shfl_xor(v, 1); v += __shfl_xor(v, 2); v += __shfl_xor(v, 4); v += __shfl_xor(v, 8); return v; }
; template <int NKB>
; DI void attn_unit(const Params& p, int l, int mode, int grp, int head, int r0, int dil, int i0, int sub_len, int W, h16* lds) {
;     ...
;   for (int kb = 0; kb < NKB; ++kb) {
;     const int j0 = i0 - W + 64 * kb;
;     const bool inr = (j0 >= 0) && (j0 < sub_len);
;     __syncthreads();
;     img_store_nat(Ki, lrow, seg, pk0, pk1);
;     img_store_T(Vt, lrow, seg, pv0, pv1);
;     __syncthreads();
;     if (kb + 1 < NKB) ATT_PREFETCH(kb + 1);
;     f4v S[4];
; #pragma unroll
;     for (int i = 0; i < 4; ++i) S[i] = (f4v){0.f, 0.f, 0.f, 0.f};
;     mm64(Qi, Ki, S, w, lane);
;     ...
; #pragma unroll
;     for (int rg = 0; rg < 4; ++rg) {
;       const float mn = fmaxf(mrow[rg], mx[rg]);
;       al[rg] = __expf(mrow[rg] - mn);
;       mrow[rg] = mn;
;       float rs_ = 0.f;
; #pragma unroll
;       for (int nt = 0; nt < 4; ++nt) {
;         float pv = vm[nt][rg] ? __expf(S[nt][rg] - mn) : 0.f;
;         rs_ += pv;
;         Pi[(16 * w + 4 * q + rg) * LDH + 16 * nt + r] = (h16)pv;
;       }
;       rsum[rg] = grp16_sum(rs_);
;       lsum[rg] = lsum[rg] * al[rg] + rsum[rg];
;     }
; #pragma unroll
;     for (int et = 0; et < 4; ++et)
; #pragma unroll
;       for (int rg = 0; rg < 4; ++rg) O[et][rg] *= al[rg];
;     __syncthreads();
;     mm64(Pi, Vt, O, w, lane);
;   }
	v_max_f32_e32 v179, v179, v201
	v_mov_b32_e32 v201, v179
	s_nop 1
	v_permlane32_swap_b32 v201, v179
	s_nop 1
	v_max3_f32 v179, v179, v201, v176
	v_sub_f32_e32 v178, v176, v179
	v_mul_f32_e32 v178, 0x3fb8aa3b, v178
	v_exp_f32_e32 v178, v178
	v_mov_b32_e32 v176, v179
	v_mul_f32_e32 v202, 0xbfb8aa3b, v179
	v_mov_b32_e32 v203, 0x3fb8aa3b
	v_fma_f32 v114, v114, v203, v202
	v_fma_f32 v115, v115, v203, v202
	v_fma_f32 v116, v116, v203, v202
	v_fma_f32 v117, v117, v203, v202
	v_fma_f32 v118, v118, v203, v202
	v_fma_f32 v119, v119, v203, v202
	v_fma_f32 v120, v120, v203, v202
	v_fma_f32 v121, v121, v203, v202
	v_fma_f32 v122, v122, v203, v202
	v_fma_f32 v123, v123, v203, v202
	v_fma_f32 v124, v124, v203, v202
	v_fma_f32 v125, v125, v203, v202
	v_fma_f32 v126, v126, v203, v202
	v_fma_f32 v127, v127, v203, v202
	v_fma_f32 v128, v128, v203, v202
	v_fma_f32 v129, v129, v203, v202
	v_exp_f32_e32 v114, v114
	v_exp_f32_e32 v115, v115
	v_exp_f32_e32 v116, v116
	v_exp_f32_e32 v117, v117
	v_exp_f32_e32 v118, v118
	v_exp_f32_e32 v119, v119
	v_exp_f32_e32 v120, v120
	v_exp_f32_e32 v121, v121
	v_exp_f32_e32 v122, v122
	v_exp_f32_e32 v123, v123
	v_exp_f32_e32 v124, v124
	v_exp_f32_e32 v125, v125
	v_exp_f32_e32 v126, v126
	v_exp_f32_e32 v127, v127
	v_exp_f32_e32 v128, v128
	v_exp_f32_e32 v129, v129
	s_nop 0
	v_fma_f32 v177, v177, v178, v114
	v_add_f32_e32 v177, v177, v115
	v_add_f32_e32 v177, v177, v116
	v_add_f32_e32 v177, v177, v117
	v_add_f32_e32 v177, v177, v118
	v_add_f32_e32 v177, v177, v119
	v_add_f32_e32 v177, v177, v120
	v_add_f32_e32 v177, v177, v121
	v_add_f32_e32 v177, v177, v122
	v_add_f32_e32 v177, v177, v123
	v_add_f32_e32 v177, v177, v124
	v_add_f32_e32 v177, v177, v125
	v_add_f32_e32 v177, v177, v126
	v_add_f32_e32 v177, v177, v127
	v_add_f32_e32 v177, v177, v128
	v_add_f32_e32 v177, v177, v129
	v_cvt_pk_f16_f32 v130, v114, v115
	v_cvt_pk_f16_f32 v131, v116, v117
	v_cvt_pk_f16_f32 v132, v118, v119
	v_cvt_pk_f16_f32 v133, v120, v121
	v_cvt_pk_f16_f32 v134, v122, v123
	v_cvt_pk_f16_f32 v135, v124, v125
	v_cvt_pk_f16_f32 v136, v126, v127
	v_cvt_pk_f16_f32 v137, v128, v129
	v_pk_mul_f32 v[138:139], v[138:139], v[178:179] op_sel_hi:[1,0]
	v_pk_mul_f32 v[140:141], v[140:141], v[178:179] op_sel_hi:[1,0]
	v_pk_mul_f32 v[142:143], v[142:143], v[178:179] op_sel_hi:[1,0]
	v_pk_mul_f32 v[144:145], v[144:145], v[178:179] op_sel_hi:[1,0]
	v_pk_mul_f32 v[146:147], v[146:147], v[178:179] op_sel_hi:[1,0]
	v_pk_mul_f32 v[148:149], v[148:149], v[178:179] op_sel_hi:[1,0]
	v_pk_mul_f32 v[150:151], v[150:151], v[178:179] op_sel_hi:[1,0]
	v_pk_mul_f32 v[152:153], v[152:153], v[178:179] op_sel_hi:[1,0]
	s_nop 1
	v_mfma_f32_16x16x32_f16 v[138:141], v[216:219], v[130:133], v[138:141]
	v_mfma_f32_16x16x32_f16 v[142:145], v[224:227], v[130:133], v[142:145]
	v_mfma_f32_16x16x32_f16 v[146:149], v[232:235], v[130:133], v[146:149]
	v_mfma_f32_16x16x32_f16 v[150:153], v[240:243], v[130:133], v[150:153]
	v_mfma_f32_16x16x32_f16 v[138:141], v[220:223], v[134:137], v[138:141]
	v_mfma_f32_16x16x32_f16 v[142:145], v[228:231], v[134:137], v[142:145]
	v_mfma_f32_16x16x32_f16 v[146:149], v[236:239], v[134:137], v[146:149]
	v_mfma_f32_16x16x32_f16 v[150:153], v[244:247], v[134:137], v[150:153]
.Lat0_kb1_end:
	s_waitcnt vmcnt(0)
	ds_write_b128 v158, v[50:53] offset:36864
	ds_write_b128 v158, v[54:57] offset:38016
	ds_write_b128 v158, v[58:61] offset:46080
	ds_write_b128 v158, v[62:65] offset:47232
	s_waitcnt lgkmcnt(0)
	s_barrier
	s_cmp_eq_u32 s4, 1
	s_cbranch_scc0 .Lat0_kb2_end
	ds_read_b128 v[18:21], v8 offset:36864
	ds_read_b128 v[22:25], v8 offset:36928
	ds_read_b128 v[26:29], v8 offset:39168
	ds_read_b128 v[30:33], v8 offset:39232
	ds_read_b128 v[34:37], v8 offset:41472
	ds_read_b128 v[38:41], v8 offset:41536
	ds_read_b128 v[42:45], v8 offset:43776
	ds_read_b128 v[46:49], v8 offset:43840
	ds_read_b64_tr_b16 v[216:217], v159 offset:36864
	ds_read_b64_tr_b16 v[218:219], v159 offset:39168
	ds_read_b64_tr_b16 v[220:221], v159 offset:41472
	ds_read_b64_tr_b16 v[222:223], v159 offset:43776
	ds_read_b64_tr_b16 v[224:225], v159 offset:36896
	ds_read_b64_tr_b16 v[226:227], v159 offset:39200
	ds_read_b64_tr_b16 v[228:229], v159 offset:41504
	ds_read_b64_tr_b16 v[230:231], v159 offset:43808
	ds_read_b64_tr_b16 v[232:233], v159 offset:36928
	ds_read_b64_tr_b16 v[234:235], v159 offset:39232
	ds_read_b64_tr_b16 v[236:237], v159 offset:41536
	ds_read_b64_tr_b16 v[238:239], v159 offset:43840
	ds_read_b64_tr_b16 v[240:241], v159 offset:36960
	ds_read_b64_tr_b16 v[242:243], v159 offset:39264
	ds_read_b64_tr_b16 v[244:245], v159 offset:41568
	ds_read_b64_tr_b16 v[246:247], v159 offset:43872
	s_waitcnt lgkmcnt(15)
; DI float grp16_sum(float v) { v += __shfl_xor(v, 1); v += __shfl_xor(v, 2); v += __shfl_xor(v, 4); v += __shfl_xor(v, 8); return v; }
; DI float grp16_max(float v) { v = fmaxf(v, __shfl_xor(v, 1)); v = fmaxf(v, __shfl_xor(v, 2)); v = fmaxf(v, __shfl_xor(v, 4)); v = fmaxf(v, __shfl_xor(v, 8)); return v; }
; template <int NKB>
; DI void attn_unit(const Params& p, int l, int mode, int grp, int head, int r0, int dil, int i0, int sub_len, int W, h16* lds) {
;     ...
;     float mx[4], al[4], rsum[4];
;     bool vm[4][4];
; #pragma unroll
;     for (int rg = 0; rg < 4; ++rg) {
;       const int row = 16 * w + 4 * q + rg;
;       float m_ = -1e30f;
; #pragma unroll
;       for (int nt = 0; nt < 4; ++nt) {
;         const int key = 16 * nt + r;
;         const int delta = row - key + W - 64 * kb;
;         const bool ok = inr && (delta >= -W) && (delta <= W);
;         vm[nt][rg] = ok;
;         float s = S[nt][rg] * 0.125f;
;         S[nt][rg] = s;
;         if (ok) m_ = fmaxf(m_, s);
;       }
;       mx[rg] = grp16_max(m_);
;     }
; #pragma unroll
;     for (int rg = 0; rg < 4; ++rg) {
;       const float mn = fmaxf(mrow[rg], mx[rg]);
;       al[rg] = __expf(mrow[rg] - mn);
;       mrow[rg] = mn;
;       float rs_ = 0.f;
; #pragma unroll
;       for (int nt = 0; nt < 4; ++nt) {
;         float pv = vm[nt][rg] ? __expf(S[nt][rg] - mn) : 0.f;
;         rs_ += pv;
;         Pi[(16 * w + 4 * q + rg) * LDH + 16 * nt + r] = (h16)pv;
;       }
;       rsum[rg] = grp16_sum(rs_);
;       lsum[rg] = lsum[rg] * al[rg] + rsum[rg];
;     }
; #pragma unroll
;     for (int et = 0; et < 4; ++et)
; #pragma unroll
;       for (int rg = 0; rg < 4; ++rg) O[et][rg] *= al[rg];
;     __syncthreads();
;     mm64(Pi, Vt, O, w, lane);
;   }
	v_mfma_f32_16x16x32_f16 v[114:117], v[18:21], v[10:13], 0
	v_mfma_f32_16x16x32_f16 v[118:121], v[26:29], v[10:13], 0
	v_mfma_f32_16x16x32_f16 v[122:125], v[34:37], v[10:13], 0
	v_mfma_f32_16x16x32_f16 v[126:129], v[42:45], v[10:13], 0
	v_mfma_f32_16x16x32_f16 v[114:117], v[22:25], v[14:17], v[114:117]
	v_mfma_f32_16x16x32_f16 v[118:121], v[30:33], v[14:17], v[118:121]
	v_mfma_f32_16x16x32_f16 v[122:125], v[38:41], v[14:17], v[122:125]
	v_mfma_f32_16x16x32_f16 v[126:129], v[46:49], v[14:17], v[126:129]
	s_nop 7
	s_nop 7
	v_mul_f32_e32 v114, 0x3e000000, v114
	v_mul_f32_e32 v115, 0x3e000000, v115
	v_mul_f32_e32 v116, 0x3e000000, v116
	v_mul_f32_e32 v117, 0x3e000000, v117
	v_mul_f32_e32 v118, 0x3e000000, v118
	v_mul_f32_e32 v119, 0x3e000000, v119
	v_mul_f32_e32 v120, 0x3e000000, v120
	v_mul_f32_e32 v121, 0x3e000000, v121
	v_mul_f32_e32 v122, 0x3e000000, v122
	v_mul_f32_e32 v123, 0x3e000000, v123
	v_mul_f32_e32 v124, 0x3e000000, v124
	v_mul_f32_e32 v125, 0x3e000000, v125
	v_mul_f32_e32 v126, 0x3e000000, v126
	v_mul_f32_e32 v127, 0x3e000000, v127
	v_mul_f32_e32 v128, 0x3e000000, v128
	v_mul_f32_e32 v129, 0x3e000000, v129
	v_mov_b32_e32 v200, 0xf149f2ca
	v_cmp_ge_i32_e32 vcc, 0, v160
	v_cndmask_b32_e32 v114, v200, v114, vcc
	v_cmp_ge_i32_e32 vcc, -1, v160
	v_cndmask_b32_e32 v115, v200, v115, vcc
	v_cmp_ge_i32_e32 vcc, -2, v160
	v_cndmask_b32_e32 v116, v200, v116, vcc
	v_cmp_ge_i32_e32 vcc, -3, v160
	v_cndmask_b32_e32 v117, v200, v117, vcc
	v_cmp_ge_i32_e32 vcc, -16, v160
	v_cndmask_b32_e32 v118, v200, v118, vcc
	v_cmp_ge_i32_e32 vcc, -17, v160
	v_cndmask_b32_e32 v119, v200, v119, vcc
	v_cmp_ge_i32_e32 vcc, -18, v160
	v_cndmask_b32_e32 v120, v200, v120, vcc
	v_cmp_ge_i32_e32 vcc, -19, v160
	v_cndmask_b32_e32 v121, v200, v121, vcc
	v_cmp_ge_i32_e32 vcc, -32, v160
	v_cndmask_b32_e32 v122, v200, v122, vcc
	v_cmp_ge_i32_e32 vcc, -33, v160
	v_cndmask_b32_e32 v123, v200, v123, vcc
	v_cmp_ge_i32_e32 vcc, -34, v160
	v_cndmask_b32_e32 v124, v200, v124, vcc
	v_cmp_ge_i32_e32 vcc, -35, v160
	v_cndmask_b32_e32 v125, v200, v125, vcc
	v_cmp_ge_i32_e32 vcc, -48, v160
	v_cndmask_b32_e32 v126, v200, v126, vcc
	v_cmp_ge_i32_e32 vcc, -49, v160
	v_cndmask_b32_e32 v127, v200, v127, vcc
	v_cmp_ge_i32_e32 vcc, -50, v160
	v_cndmask_b32_e32 v128, v200, v128, vcc
	v_cmp_ge_i32_e32 vcc, -51, v160
	v_cndmask_b32_e32 v129, v200, v129, vcc
	v_max3_f32 v179, v114, v115, v116
	v_max3_f32 v179, v179, v117, v118
	v_max3_f32 v179, v179, v119, v120
	v_max3_f32 v179, v179, v121, v122
	v_max3_f32 v179, v179, v123, v124
	v_max3_f32 v179, v179, v125, v126
	v_max3_f32 v179, v179, v127, v128
	v_max_f32_e32 v179, v179, v129
	ds_bpermute_b32 v201, v174, v179
	s_waitcnt lgkmcnt(0)
	v_max_f32_e32 v179, v179, v201
	v_mov_b32_e32 v201, v179
	s_nop 1
	v_permlane32_swap_b32 v201, v179
	s_nop 1
	v_max3_f32 v179, v179, v201, v176
	v_sub_f32_e32 v178, v176, v179
	v_mul_f32_e32 v178, 0x3fb8aa3b, v178
	v_exp_f32_e32 v178, v178
	v_mov_b32_e32 v176, v179
	v_mul_f32_e32 v202, 0xbfb8aa3b, v179
	v_mov_b32_e32 v203, 0x3fb8aa3b
	v_fma_f32 v114, v114, v203, v202
	v_fma_f32 v115, v115, v203, v202
	v_fma_f32 v116, v116, v203, v202
	v_fma_f32 v117, v117, v203, v202
	v_fma_f32 v118, v118, v203, v202
	v_fma_f32 v119, v119, v203, v202
	v_fma_f32 v120, v120, v203, v202
	v_fma_f32 v121, v121, v203, v202
	v_fma_f32 v122, v122, v203, v202
	v_fma_f32 v123, v123, v203, v202
	v_fma_f32 v124, v124, v203, v202
	v_fma_f32 v125, v125, v203, v202
	v_fma_f32 v126, v126, v203, v202
	v_fma_f32 v127, v127, v203, v202
	v_fma_f32 v128, v128, v203, v202
	v_fma_f32 v129, v129, v203, v202
	v_exp_f32_e32 v114, v114
	v_exp_f32_e32 v115, v115
	v_exp_f32_e32 v116, v116
	v_exp_f32_e32 v117, v117
	v_exp_f32_e32 v118, v118
	v_exp_f32_e32 v119, v119
	v_exp_f32_e32 v120, v120
	v_exp_f32_e32 v121, v121
	v_exp_f32_e32 v122, v122
	v_exp_f32_e32 v123, v123
	v_exp_f32_e32 v124, v124
	v_exp_f32_e32 v125, v125
	v_exp_f32_e32 v126, v126
	v_exp_f32_e32 v127, v127
	v_exp_f32_e32 v128, v128
	v_exp_f32_e32 v129, v129
	s_nop 0
	v_fma_f32 v177, v177, v178, v114
	v_add_f32_e32 v177, v177, v115
	v_add_f32_e32 v177, v177, v116
	v_add_f32_e32 v177, v177, v117
	v_add_f32_e32 v177, v177, v118
	v_add_f32_e32 v177, v177, v119
	v_add_f32_e32 v177, v177, v120
	v_add_f32_e32 v177, v177, v121
	v_add_f32_e32 v177, v177, v122
	v_add_f32_e32 v177, v177, v123
	v_add_f32_e32 v177, v177, v124
	v_add_f32_e32 v177, v177, v125
	v_add_f32_e32 v177, v177, v126
	v_add_f32_e32 v177, v177, v127
	v_add_f32_e32 v177, v177, v128
	v_add_f32_e32 v177, v177, v129
	v_cvt_pk_f16_f32 v130, v114, v115
	v_cvt_pk_f16_f32 v131, v116, v117
	v_cvt_pk_f16_f32 v132, v118, v119
	v_cvt_pk_f16_f32 v133, v120, v121
	v_cvt_pk_f16_f32 v134, v122, v123
	v_cvt_pk_f16_f32 v135, v124, v125
	v_cvt_pk_f16_f32 v136, v126, v127
	v_cvt_pk_f16_f32 v137, v128, v129
	v_pk_mul_f32 v[138:139], v[138:139], v[178:179] op_sel_hi:[1,0]
	v_pk_mul_f32 v[140:141], v[140:141], v[178:179] op_sel_hi:[1,0]
	v_pk_mul_f32 v[142:143], v[142:143], v[178:179] op_sel_hi:[1,0]
	v_pk_mul_f32 v[144:145], v[144:145], v[178:179] op_sel_hi:[1,0]
	v_pk_mul_f32 v[146:147], v[146:147], v[178:179] op_sel_hi:[1,0]
	v_pk_mul_f32 v[148:149], v[148:149], v[178:179] op_sel_hi:[1,0]
	v_pk_mul_f32 v[150:151], v[150:151], v[178:179] op_sel_hi:[1,0]
	v_pk_mul_f32 v[152:153], v[152:153], v[178:179] op_sel_hi:[1,0]
	s_nop 1
	v_mfma_f32_16x16x32_f16 v[138:141], v[216:219], v[130:133], v[138:141]
	v_mfma_f32_16x16x32_f16 v[142:145], v[224:227], v[130:133], v[142:145]
	v_mfma_f32_16x16x32_f16 v[146:149], v[232:235], v[130:133], v[146:149]
	v_mfma_f32_16x16x32_f16 v[150:153], v[240:243], v[130:133], v[150:153]
	v_mfma_f32_16x16x32_f16 v[138:141], v[220:223], v[134:137], v[138:141]
	v_mfma_f32_16x16x32_f16 v[142:145], v[228:231], v[134:137], v[142:145]
	v_mfma_f32_16x16x32_f16 v[146:149], v[236:239], v[134:137], v[146:149]
	v_mfma_f32_16x16x32_f16 v[150:153], v[244:247], v[134:137], v[150:153]
; DI int otid() { int t = threadIdx.x & 255; asm volatile("" : "+v"(t)); return t; }
; template <int NKB>
; DI void attn_unit(const Params& p, int l, int mode, int grp, int head, int r0, int dil, int i0, int sub_len, int W, h16* lds) {
;   unsigned char* ws = p.ws;
;   const h16* P = (const h16*)(ws + OFF_PS);
;   h16* Qi = lds; h16* Ki = lds + 64 * LDH; h16* Vt = lds + 128 * LDH; h16* Pi = lds + 192 * LDH;
;   const int tid = otid(), lane = tid & 63, w = tid >> 6, r = lane & 15, q = lane >> 4;
;   const int lrow = tid >> 2, seg = tid & 3;
;   int qcol, kcol, vcol;
;   if (mode == 0) { qcol = 1024 + grp * 256 + head * 64; kcol = 1792 + grp * 256 + head * 64; vcol = 2560 + grp * 256 + head * 64; }
;   else { qcol = 4352 + head * 64; kcol = 4864 + (head >> 2) * 64; vcol = 4992 + (head >> 2) * 64; }
;   __syncthreads();
;   {
;     const size_t pos = (size_t)r0 + (size_t)dil * (i0 + lrow);
;     const h16* g = P + pos * NSM + qcol + 16 * seg;
;     img_store_nat(Qi, lrow, seg, *(const u4v*)g, *(const u4v*)(g + 8));
;   }
;   float mrow[4], lsum[4];
;   f4v O[4];
;   float m_init = -1e30f, l_init = 0.f;
;   if (mode == 1) { m_init = p.d_sink[l * 8 + head]; l_init = 1.f; }
; #pragma unroll
;   for (int i = 0; i < 4; ++i) { mrow[i] = m_init; lsum[i] = l_init; O[i] = (f4v){0.f, 0.f, 0.f, 0.f}; }
;   u4v pk0, pk1, pv0, pv1;
;     ...
;   ATT_PREFETCH(0);
;     ...
; #pragma unroll
;   for (int rg = 0; rg < 4; ++rg) {
;     const int row = 16 * w + 4 * q + rg;
;     const size_t pos = (size_t)r0 + (size_t)dil * (i0 + row);
;     const float inv = 1.f / lsum[rg];
;     if (mode == 0) {
;       h16* ob = (h16*)(ws + OFF_OB) + ((size_t)grp * SEQ + pos) * 256 + head * 64;
; #pragma unroll
;       for (int et = 0; et < 4; ++et) ob[16 * et + r] = (h16)(O[et][rg] * inv);
;       if (r == 0) {
;         float* ml = (float*)(ws + OFF_MLB) + (((size_t)grp * SEQ + pos) * 4 + head) * 2;
;         ml[0] = mrow[rg]; ml[1] = lsum[rg];
;       }
;     } else {
;       h16* y = (h16*)(ws + OFF_Y) + pos * 1280 + 768 + head * 64;
; #pragma unroll
;       for (int et = 0; et < 4; ++et) y[16 * et + r] = (h16)(O[et][rg] * inv);
;     }
;   }
.Lat0_kb2_end:
	s_nop 7
	s_nop 1
	ds_bpermute_b32 v201, v174, v177
	s_waitcnt lgkmcnt(0)
	v_add_f32_e32 v177, v177, v201
	v_mov_b32_e32 v201, v177
	s_nop 1
	v_permlane32_swap_b32 v201, v177
	s_nop 1
	v_add_f32_e32 v177, v177, v201
	v_rcp_f32_e32 v178, v177
	s_nop 0
	v_pk_mul_f32 v[138:139], v[138:139], v[178:179] op_sel_hi:[1,0]
	v_pk_mul_f32 v[140:141], v[140:141], v[178:179] op_sel_hi:[1,0]
	v_pk_mul_f32 v[142:143], v[142:143], v[178:179] op_sel_hi:[1,0]
	v_pk_mul_f32 v[144:145], v[144:145], v[178:179] op_sel_hi:[1,0]
	v_pk_mul_f32 v[146:147], v[146:147], v[178:179] op_sel_hi:[1,0]
	v_pk_mul_f32 v[148:149], v[148:149], v[178:179] op_sel_hi:[1,0]
	v_pk_mul_f32 v[150:151], v[150:151], v[178:179] op_sel_hi:[1,0]
	v_pk_mul_f32 v[152:153], v[152:153], v[178:179] op_sel_hi:[1,0]
	v_cvt_pk_f16_f32 v130, v138, v139
	v_cvt_pk_f16_f32 v131, v140, v141
	v_cvt_pk_f16_f32 v132, v142, v143
	v_cvt_pk_f16_f32 v133, v144, v145
	v_cvt_pk_f16_f32 v134, v146, v147
	v_cvt_pk_f16_f32 v135, v148, v149
	v_cvt_pk_f16_f32 v136, v150, v151
	v_cvt_pk_f16_f32 v137, v152, v153
	global_store_dwordx2 v249, v[130:131], s[48:49]
	global_store_dwordx2 v249, v[132:133], s[48:49] offset:32
	global_store_dwordx2 v249, v[134:135], s[48:49] offset:64
	global_store_dwordx2 v249, v[136:137], s[48:49] offset:96
	v_and_b32_e32 v179, 63, v182
	v_and_b32_e32 v200, 15, v179
	s_lshl_b32 s51, s58, 4
	v_add_u32_e32 v200, s51, v200
	s_lshl_b32 s51, s60, 5
	v_mul_u32_u24_e32 v200, s51, v200
	v_mov_b32_e32 v202, v176
	v_mov_b32_e32 v203, v177
	s_mov_b64 exec, 0xffff
	s_nop 1
	global_store_dwordx2 v200, v[202:203], s[16:17]
	s_nop 1
	s_mov_b64 exec, -1
.LBB0_909:
.LBB0_910:
	s_andn2_saveexec_b64 s[34:35], s[34:35]
	s_cbranch_execz .LBB0_914
	v_readfirstlane_b32 s36, v1
	v_readfirstlane_b32 s58, v182
	s_lshr_b32 s58, s58, 6
	s_sub_u32 s51, s36, 0xa8
	s_and_b32 s56, s51, 15
	s_sub_u32 s56, s56, 8
	s_and_b32 s56, s56, 15
	s_lshr_b32 s56, s56, 1
	s_lshr_b32 s57, s51, 4
	s_lshl_b32 s57, s57, 1
	s_and_b32 s59, s51, 1
	s_or_b32 s57, s57, s59
	s_lshl_b32 s56, s56, 8
	s_add_u32 s36, s56, s57
	s_and_b32 s37, s36, 7
	s_lshr_b32 s38, s36, 3
	s_lshl_b32 s38, s38, 6
	s_mov_b32 s40, 0
	s_movk_i32 s39, 0x2800
	s_mov_b32 s60, 1
	s_movk_i32 s41, 0x4000
	s_lshr_b32 s51, s37, 2
	s_lshl_b32 s51, s51, 7
	s_lshl_b32 s56, s37, 7
	s_add_u32 s53, s56, 0x2200
	s_add_u32 s54, s51, 0x2600
	s_add_u32 s55, s51, 0x2700
	v_and_b32_e32 v179, 63, v182
	v_and_b32_e32 v200, 15, v179
	v_lshrrev_b32_e32 v201, 4, v179
	v_lshlrev_b32_e32 v202, 4, v201
	v_mad_u32_u24 v2, v200, s39, v202
	v_add_u32_e32 v203, 16, v200
	v_mad_u32_u24 v3, v203, s39, v202
	v_add_u32_e32 v203, 32, v200
	v_mad_u32_u24 v4, v203, s39, v202
	v_add_u32_e32 v203, 48, v200
	v_mad_u32_u24 v5, v203, s39, v202
	s_lshl_b32 s51, s58, 4
	v_add_u32_e32 v203, s51, v200
	v_mad_u32_u24 v248, v203, s39, v202
	v_lshlrev_b32_e32 v160, 2, v201
	v_sub_u32_e32 v160, v160, v203
	v_mul_u32_u24_e32 v249, 0xa00, v203
	v_lshl_add_u32 v249, v201, 3, v249
	v_lshrrev_b32_e32 v203, 3, v179
	s_lshl_b32 s51, s58, 4
	v_add_u32_e32 v203, s51, v203
	v_and_b32_e32 v202, 7, v179
	v_lshlrev_b32_e32 v202, 4, v202
	v_mad_u32_u24 v6, v203, s39, v202
	v_add_u32_e32 v200, 8, v203
	v_mad_u32_u24 v7, v200, s39, v202
	s_movk_i32 s57, 0x90
	v_mad_u32_u24 v158, v203, s57, v183
	v_add_u32_e32 v158, v158, v202
	v_and_b32_e32 v200, 15, v179
	v_mad_u32_u24 v8, v200, s57, v183
	v_lshl_add_u32 v8, v201, 4, v8
	v_lshrrev_b32_e32 v203, 2, v179
	v_mad_u32_u24 v159, v203, s57, v183
	v_and_b32_e32 v203, 3, v179
	v_lshl_add_u32 v159, v203, 3, v159
	v_add_u32_e32 v159, 0x2400, v159
	v_xor_b32_e32 v174, 16, v179
	v_lshlrev_b32_e32 v174, 2, v174
	v_xor_b32_e32 v175, 32, v179
	v_lshlrev_b32_e32 v175, 2, v175
	s_mul_i32 s51, s60, s38
	s_add_u32 s51, s51, s40
	s_mul_i32 s56, s51, 0x2800
	s_add_u32 s56, s56, s53
	s_add_u32 s42, s0, s56
	s_addc_u32 s43, s1, 0
	global_load_dwordx4 v[10:13], v248, s[42:43]
	global_load_dwordx4 v[14:17], v248, s[42:43] offset:64
	v_readlane_b32 s48, v252, 7
	v_readlane_b32 s49, v252, 8
	s_mul_i32 s56, s38, 0xa00
	s_lshl_b32 s57, s37, 7
	s_add_u32 s56, s56, s57
	s_add_u32 s56, s56, 0x11a80600
	s_nop 2
	s_add_u32 s48, s48, s56
	s_addc_u32 s49, s49, 0
	v_readlane_b32 s18, v252, 27
	v_readlane_b32 s19, v252, 28
	s_or_b32 s56, s92, s37
	s_lshl_b32 s56, s56, 2
	s_nop 3
	s_add_u32 s18, s18, s56
	s_addc_u32 s19, s19, 0
	s_load_dword s56, s[18:19], 0x0
	v_cmp_gt_u32_e32 vcc, 16, v179
	v_cndmask_b32_e64 v177, 0, 1.0, vcc
	s_waitcnt lgkmcnt(0)
	v_mov_b32_e32 v176, s56
	v_mov_b32_e32 v138, 0
	v_mov_b32_e32 v139, 0
	v_mov_b32_e32 v140, 0
	v_mov_b32_e32 v141, 0
	v_mov_b32_e32 v142, 0
	v_mov_b32_e32 v143, 0
	v_mov_b32_e32 v144, 0
	v_mov_b32_e32 v145, 0
	v_mov_b32_e32 v146, 0
	v_mov_b32_e32 v147, 0
	v_mov_b32_e32 v148, 0
	v_mov_b32_e32 v149, 0
	v_mov_b32_e32 v150, 0
	v_mov_b32_e32 v151, 0
	v_mov_b32_e32 v152, 0
	v_mov_b32_e32 v153, 0
	s_sub_u32 s50, s38, 128
	s_cmp_ge_i32 s50, 0
	s_cselect_b32 s56, 1, 0
	s_cmp_lt_i32 s50, s41
	s_cselect_b32 s57, 1, 0
	s_and_b32 s2, s56, s57
	s_cmp_eq_u32 s2, 1
	s_cselect_b32 s50, s50, s38
	s_mul_i32 s50, s50, s60
	s_add_u32 s50, s50, s40
	s_mul_i32 s50, s50, 0x2800
	s_add_u32 s56, s50, s54
	s_add_u32 s44, s0, s56
	s_addc_u32 s45, s1, 0
	s_add_u32 s56, s50, s55
	s_add_u32 s46, s0, s56
	s_addc_u32 s47, s1, 0
	global_load_dwordx4 v[50:53], v6, s[44:45]
	global_load_dwordx4 v[54:57], v7, s[44:45]
	global_load_dwordx4 v[58:61], v6, s[46:47]
	global_load_dwordx4 v[62:65], v7, s[46:47]
	s_sub_u32 s50, s38, 64
	s_cmp_ge_i32 s50, 0
	s_cselect_b32 s56, 1, 0
	s_cmp_lt_i32 s50, s41
	s_cselect_b32 s57, 1, 0
	s_and_b32 s3, s56, s57
	s_cmp_eq_u32 s3, 1
	s_cselect_b32 s50, s50, s38
	s_mul_i32 s50, s50, s60
	s_add_u32 s50, s50, s40
	s_mul_i32 s50, s50, 0x2800
	s_add_u32 s56, s50, s54
	s_add_u32 s44, s0, s56
	s_addc_u32 s45, s1, 0
	s_add_u32 s56, s50, s55
	s_add_u32 s46, s0, s56
	s_addc_u32 s47, s1, 0
	global_load_dwordx4 v[66:69], v6, s[44:45]
	global_load_dwordx4 v[70:73], v7, s[44:45]
	global_load_dwordx4 v[74:77], v6, s[46:47]
	global_load_dwordx4 v[78:81], v7, s[46:47]
	s_waitcnt vmcnt(4)
	ds_write_b128 v158, v[50:53] offset:0
	ds_write_b128 v158, v[54:57] offset:1152
	ds_write_b128 v158, v[58:61] offset:9216
	ds_write_b128 v158, v[62:65] offset:10368
	s_waitcnt lgkmcnt(0)
	s_barrier
; DI float grp16_max(float v) { v = fmaxf(v, __shfl_xor(v, 1)); v = fmaxf(v, __shfl_xor(v, 2)); v = fmaxf(v, __shfl_xor(v, 4)); v = fmaxf(v, __shfl_xor(v, 8)); return v; }
; template <int NKB>
; DI void attn_unit(const Params& p, int l, int mode, int grp, int head, int r0, int dil, int i0, int sub_len, int W, h16* lds) {
;     ...
;   for (int kb = 0; kb < NKB; ++kb) {
;     const int j0 = i0 - W + 64 * kb;
;     const bool inr = (j0 >= 0) && (j0 < sub_len);
;     __syncthreads();
;     img_store_nat(Ki, lrow, seg, pk0, pk1);
;     img_store_T(Vt, lrow, seg, pv0, pv1);
;     __syncthreads();
;     if (kb + 1 < NKB) ATT_PREFETCH(kb + 1);
;     f4v S[4];
; #pragma unroll
;     for (int i = 0; i < 4; ++i) S[i] = (f4v){0.f, 0.f, 0.f, 0.f};
;     mm64(Qi, Ki, S, w, lane);
;     float mx[4], al[4], rsum[4];
;     bool vm[4][4];
; #pragma unroll
;     for (int rg = 0; rg < 4; ++rg) {
;       const int row = 16 * w + 4 * q + rg;
;       float m_ = -1e30f;
; #pragma unroll
;       for (int nt = 0; nt < 4; ++nt) {
;         const int key = 16 * nt + r;
;         const int delta = row - key + W - 64 * kb;
;         const bool ok = inr && (delta >= -W) && (delta <= W);
;         vm[nt][rg] = ok;
;         float s = S[nt][rg] * 0.125f;
;         S[nt][rg] = s;
;         if (ok) m_ = fmaxf(m_, s);
;       }
;       mx[rg] = grp16_max(m_);
;     }
	s_add_u32 s50, s38, 0
	s_cmp_ge_i32 s50, 0
	s_cselect_b32 s56, 1, 0
	s_cmp_lt_i32 s50, s41
	s_cselect_b32 s57, 1, 0
	s_and_b32 s4, s56, s57
	s_cmp_eq_u32 s4, 1
	s_cselect_b32 s50, s50, s38
	s_mul_i32 s50, s50, s60
	s_add_u32 s50, s50, s40
	s_mul_i32 s50, s50, 0x2800
	s_add_u32 s56, s50, s54
	s_add_u32 s44, s0, s56
	s_addc_u32 s45, s1, 0
	s_add_u32 s56, s50, s55
	s_add_u32 s46, s0, s56
	s_addc_u32 s47, s1, 0
	global_load_dwordx4 v[50:53], v6, s[44:45]
	global_load_dwordx4 v[54:57], v7, s[44:45]
	global_load_dwordx4 v[58:61], v6, s[46:47]
	global_load_dwordx4 v[62:65], v7, s[46:47]
	s_cmp_eq_u32 s2, 1
	s_cbranch_scc0 .Lat1_kb0_end
	ds_read_b128 v[18:21], v8 offset:0
	ds_read_b128 v[22:25], v8 offset:64
	ds_read_b128 v[26:29], v8 offset:2304
	ds_read_b128 v[30:33], v8 offset:2368
	ds_read_b128 v[34:37], v8 offset:4608
	ds_read_b128 v[38:41], v8 offset:4672
	ds_read_b128 v[42:45], v8 offset:6912
	ds_read_b128 v[46:49], v8 offset:6976
	ds_read_b64_tr_b16 v[216:217], v159
	ds_read_b64_tr_b16 v[218:219], v159 offset:2304
	ds_read_b64_tr_b16 v[220:221], v159 offset:4608
	ds_read_b64_tr_b16 v[222:223], v159 offset:6912
	ds_read_b64_tr_b16 v[224:225], v159 offset:32
	ds_read_b64_tr_b16 v[226:227], v159 offset:2336
	ds_read_b64_tr_b16 v[228:229], v159 offset:4640
	ds_read_b64_tr_b16 v[230:231], v159 offset:6944
	ds_read_b64_tr_b16 v[232:233], v159 offset:64
	ds_read_b64_tr_b16 v[234:235], v159 offset:2368
	ds_read_b64_tr_b16 v[236:237], v159 offset:4672
	ds_read_b64_tr_b16 v[238:239], v159 offset:6976
	ds_read_b64_tr_b16 v[240:241], v159 offset:96
	ds_read_b64_tr_b16 v[242:243], v159 offset:2400
	ds_read_b64_tr_b16 v[244:245], v159 offset:4704
	ds_read_b64_tr_b16 v[246:247], v159 offset:7008
	s_waitcnt lgkmcnt(15)
	v_mfma_f32_16x16x32_f16 v[114:117], v[18:21], v[10:13], 0
	v_mfma_f32_16x16x32_f16 v[118:121], v[26:29], v[10:13], 0
	v_mfma_f32_16x16x32_f16 v[122:125], v[34:37], v[10:13], 0
	v_mfma_f32_16x16x32_f16 v[126:129], v[42:45], v[10:13], 0
	v_mfma_f32_16x16x32_f16 v[114:117], v[22:25], v[14:17], v[114:117]
	v_mfma_f32_16x16x32_f16 v[118:121], v[30:33], v[14:17], v[118:121]
	v_mfma_f32_16x16x32_f16 v[122:125], v[38:41], v[14:17], v[122:125]
	v_mfma_f32_16x16x32_f16 v[126:129], v[46:49], v[14:17], v[126:129]
	s_nop 7
	s_nop 7
	v_mul_f32_e32 v114, 0x3e000000, v114
	v_mul_f32_e32 v115, 0x3e000000, v115
	v_mul_f32_e32 v116, 0x3e000000, v116
	v_mul_f32_e32 v117, 0x3e000000, v117
	v_mul_f32_e32 v118, 0x3e000000, v118
	v_mul_f32_e32 v119, 0x3e000000, v119
	v_mul_f32_e32 v120, 0x3e000000, v120
	v_mul_f32_e32 v121, 0x3e000000, v121
	v_mul_f32_e32 v122, 0x3e000000, v122
	v_mul_f32_e32 v123, 0x3e000000, v123
	v_mul_f32_e32 v124, 0x3e000000, v124
	v_mul_f32_e32 v125, 0x3e000000, v125
	v_mul_f32_e32 v126, 0x3e000000, v126
	v_mul_f32_e32 v127, 0x3e000000, v127
	v_mul_f32_e32 v128, 0x3e000000, v128
	v_mul_f32_e32 v129, 0x3e000000, v129
	v_mov_b32_e32 v200, 0xf149f2ca
	v_cmp_le_i32_e32 vcc, 0, v160
	v_cndmask_b32_e32 v114, v200, v114, vcc
	v_cmp_le_i32_e32 vcc, -1, v160
	v_cndmask_b32_e32 v115, v200, v115, vcc
	v_cmp_le_i32_e32 vcc, -2, v160
	v_cndmask_b32_e32 v116, v200, v116, vcc
	v_cmp_le_i32_e32 vcc, -3, v160
	v_cndmask_b32_e32 v117, v200, v117, vcc
	v_cmp_le_i32_e32 vcc, -16, v160
	v_cndmask_b32_e32 v118, v200, v118, vcc
	v_cmp_le_i32_e32 vcc, -17, v160
	v_cndmask_b32_e32 v119, v200, v119, vcc
	v_cmp_le_i32_e32 vcc, -18, v160
	v_cndmask_b32_e32 v120, v200, v120, vcc
	v_cmp_le_i32_e32 vcc, -19, v160
	v_cndmask_b32_e32 v121, v200, v121, vcc
	v_cmp_le_i32_e32 vcc, -32, v160
	v_cndmask_b32_e32 v122, v200, v122, vcc
	v_cmp_le_i32_e32 vcc, -33, v160
	v_cndmask_b32_e32 v123, v200, v123, vcc
	v_cmp_le_i32_e32 vcc, -34, v160
	v_cndmask_b32_e32 v124, v200, v124, vcc
	v_cmp_le_i32_e32 vcc, -35, v160
	v_cndmask_b32_e32 v125, v200, v125, vcc
	v_cmp_le_i32_e32 vcc, -48, v160
	v_cndmask_b32_e32 v126, v200, v126, vcc
	v_cmp_le_i32_e32 vcc, -49, v160
	v_cndmask_b32_e32 v127, v200, v127, vcc
	v_cmp_le_i32_e32 vcc, -50, v160
	v_cndmask_b32_e32 v128, v200, v128, vcc
	v_cmp_le_i32_e32 vcc, -51, v160
	v_cndmask_b32_e32 v129, v200, v129, vcc
	v_max3_f32 v179, v114, v115, v116
	v_max3_f32 v179, v179, v117, v118
	v_max3_f32 v179, v179, v119, v120
	v_max3_f32 v179, v179, v121, v122
	v_max3_f32 v179, v179, v123, v124
	v_max3_f32 v179, v179, v125, v126
	v_max3_f32 v179, v179, v127, v128
	v_max_f32_e32 v179, v179, v129
	ds_bpermute_b32 v201, v174, v179
	s_waitcnt lgkmcnt(0)
; DI float grp16_sum(float v) { v += __shfl_xor(v, 1); v += __shfl_xor(v, 2); v += __shfl_xor(v, 4); v += __shfl_xor(v, 8); return v; }
; template <int NKB>
; DI void attn_unit(const Params& p, int l, int mode, int grp, int head, int r0, int dil, int i0, int sub_len, int W, h16* lds) {
;     ...
;   for (int kb = 0; kb < NKB; ++kb) {
;     const int j0 = i0 - W + 64 * kb;
;     const bool inr = (j0 >= 0) && (j0 < sub_len);
;     __syncthreads();
;     img_store_nat(Ki, lrow, seg, pk0, pk1);
;     img_store_T(Vt, lrow, seg, pv0, pv1);
;     __syncthreads();
;     if (kb + 1 < NKB) ATT_PREFETCH(kb + 1);
;     f4v S[4];
; #pragma unroll
;     for (int i = 0; i < 4; ++i) S[i] = (f4v){0.f, 0.f, 0.f, 0.f};
;     mm64(Qi, Ki, S, w, lane);
;     ...
; #pragma unroll
;     for (int rg = 0; rg < 4; ++rg) {
;       const float mn = fmaxf(mrow[rg], mx[rg]);
;       al[rg] = __expf(mrow[rg] - mn);
;       mrow[rg] = mn;
;       float rs_ = 0.f;
; #pragma unroll
;       for (int nt = 0; nt < 4; ++nt) {
;         float pv = vm[nt][rg] ? __expf(S[nt][rg] - mn) : 0.f;
;         rs_ += pv;
;         Pi[(16 * w + 4 * q + rg) * LDH + 16 * nt + r] = (h16)pv;
;       }
;       rsum[rg] = grp16_sum(rs_);
;       lsum[rg] = lsum[rg] * al[rg] + rsum[rg];
;     }
; #pragma unroll
;     for (int et = 0; et < 4; ++et)
; #pragma unroll
;       for (int rg = 0; rg < 4; ++rg) O[et][rg] *= al[rg];
;     __syncthreads();
;     mm64(Pi, Vt, O, w, lane);
;   }
	v_max_f32_e32 v179, v179, v201
	v_mov_b32_e32 v201, v179
	s_nop 1
	v_permlane32_swap_b32 v201, v179
	s_nop 1
	v_max3_f32 v179, v179, v201, v176
	v_sub_f32_e32 v178, v176, v179
	v_mul_f32_e32 v178, 0x3fb8aa3b, v178
	v_exp_f32_e32 v178, v178
	v_mov_b32_e32 v176, v179
	v_mul_f32_e32 v202, 0xbfb8aa3b, v179
	v_mov_b32_e32 v203, 0x3fb8aa3b
	v_fma_f32 v114, v114, v203, v202
	v_fma_f32 v115, v115, v203, v202
	v_fma_f32 v116, v116, v203, v202
	v_fma_f32 v117, v117, v203, v202
	v_fma_f32 v118, v118, v203, v202
	v_fma_f32 v119, v119, v203, v202
	v_fma_f32 v120, v120, v203, v202
	v_fma_f32 v121, v121, v203, v202
	v_fma_f32 v122, v122, v203, v202
	v_fma_f32 v123, v123, v203, v202
	v_fma_f32 v124, v124, v203, v202
	v_fma_f32 v125, v125, v203, v202
	v_fma_f32 v126, v126, v203, v202
	v_fma_f32 v127, v127, v203, v202
	v_fma_f32 v128, v128, v203, v202
	v_fma_f32 v129, v129, v203, v202
	v_exp_f32_e32 v114, v114
	v_exp_f32_e32 v115, v115
	v_exp_f32_e32 v116, v116
	v_exp_f32_e32 v117, v117
	v_exp_f32_e32 v118, v118
	v_exp_f32_e32 v119, v119
	v_exp_f32_e32 v120, v120
	v_exp_f32_e32 v121, v121
	v_exp_f32_e32 v122, v122
	v_exp_f32_e32 v123, v123
	v_exp_f32_e32 v124, v124
	v_exp_f32_e32 v125, v125
	v_exp_f32_e32 v126, v126
	v_exp_f32_e32 v127, v127
	v_exp_f32_e32 v128, v128
	v_exp_f32_e32 v129, v129
	s_nop 0
	v_fma_f32 v177, v177, v178, v114
	v_add_f32_e32 v177, v177, v115
	v_add_f32_e32 v177, v177, v116
	v_add_f32_e32 v177, v177, v117
	v_add_f32_e32 v177, v177, v118
	v_add_f32_e32 v177, v177, v119
	v_add_f32_e32 v177, v177, v120
	v_add_f32_e32 v177, v177, v121
	v_add_f32_e32 v177, v177, v122
	v_add_f32_e32 v177, v177, v123
	v_add_f32_e32 v177, v177, v124
	v_add_f32_e32 v177, v177, v125
	v_add_f32_e32 v177, v177, v126
	v_add_f32_e32 v177, v177, v127
	v_add_f32_e32 v177, v177, v128
	v_add_f32_e32 v177, v177, v129
	v_cvt_pk_f16_f32 v130, v114, v115
	v_cvt_pk_f16_f32 v131, v116, v117
	v_cvt_pk_f16_f32 v132, v118, v119
	v_cvt_pk_f16_f32 v133, v120, v121
	v_cvt_pk_f16_f32 v134, v122, v123
	v_cvt_pk_f16_f32 v135, v124, v125
	v_cvt_pk_f16_f32 v136, v126, v127
	v_cvt_pk_f16_f32 v137, v128, v129
	v_pk_mul_f32 v[138:139], v[138:139], v[178:179] op_sel_hi:[1,0]
	v_pk_mul_f32 v[140:141], v[140:141], v[178:179] op_sel_hi:[1,0]
	v_pk_mul_f32 v[142:143], v[142:143], v[178:179] op_sel_hi:[1,0]
	v_pk_mul_f32 v[144:145], v[144:145], v[178:179] op_sel_hi:[1,0]
	v_pk_mul_f32 v[146:147], v[146:147], v[178:179] op_sel_hi:[1,0]
	v_pk_mul_f32 v[148:149], v[148:149], v[178:179] op_sel_hi:[1,0]
	v_pk_mul_f32 v[150:151], v[150:151], v[178:179] op_sel_hi:[1,0]
	v_pk_mul_f32 v[152:153], v[152:153], v[178:179] op_sel_hi:[1,0]
	s_nop 1
	v_mfma_f32_16x16x32_f16 v[138:141], v[216:219], v[130:133], v[138:141]
	v_mfma_f32_16x16x32_f16 v[142:145], v[224:227], v[130:133], v[142:145]
	v_mfma_f32_16x16x32_f16 v[146:149], v[232:235], v[130:133], v[146:149]
	v_mfma_f32_16x16x32_f16 v[150:153], v[240:243], v[130:133], v[150:153]
	v_mfma_f32_16x16x32_f16 v[138:141], v[220:223], v[134:137], v[138:141]
	v_mfma_f32_16x16x32_f16 v[142:145], v[228:231], v[134:137], v[142:145]
	v_mfma_f32_16x16x32_f16 v[146:149], v[236:239], v[134:137], v[146:149]
	v_mfma_f32_16x16x32_f16 v[150:153], v[244:247], v[134:137], v[150:153]
.Lat1_kb0_end:
	s_waitcnt vmcnt(4)
	ds_write_b128 v158, v[66:69] offset:18432
	ds_write_b128 v158, v[70:73] offset:19584
	ds_write_b128 v158, v[74:77] offset:27648
	ds_write_b128 v158, v[78:81] offset:28800
	s_waitcnt lgkmcnt(0)
	s_barrier
	s_add_u32 s50, s38, 64
	s_cmp_ge_i32 s50, 0
	s_cselect_b32 s56, 1, 0
	s_cmp_lt_i32 s50, s41
	s_cselect_b32 s57, 1, 0
	s_and_b32 s5, s56, s57
	s_cmp_eq_u32 s5, 1
	s_cselect_b32 s50, s50, s38
	s_mul_i32 s50, s50, s60
	s_add_u32 s50, s50, s40
	s_mul_i32 s50, s50, 0x2800
	s_add_u32 s56, s50, s54
	s_add_u32 s44, s0, s56
	s_addc_u32 s45, s1, 0
	s_add_u32 s56, s50, s55
	s_add_u32 s46, s0, s56
	s_addc_u32 s47, s1, 0
	global_load_dwordx4 v[66:69], v6, s[44:45]
	global_load_dwordx4 v[70:73], v7, s[44:45]
	global_load_dwordx4 v[74:77], v6, s[46:47]
	global_load_dwordx4 v[78:81], v7, s[46:47]
	s_cmp_eq_u32 s3, 1
	s_cbranch_scc0 .Lat1_kb1_end
	ds_read_b128 v[18:21], v8 offset:18432
	ds_read_b128 v[22:25], v8 offset:18496
	ds_read_b128 v[26:29], v8 offset:20736
	ds_read_b128 v[30:33], v8 offset:20800
	ds_read_b128 v[34:37], v8 offset:23040
	ds_read_b128 v[38:41], v8 offset:23104
	ds_read_b128 v[42:45], v8 offset:25344
	ds_read_b128 v[46:49], v8 offset:25408
	ds_read_b64_tr_b16 v[216:217], v159 offset:18432
	ds_read_b64_tr_b16 v[218:219], v159 offset:20736
	ds_read_b64_tr_b16 v[220:221], v159 offset:23040
	ds_read_b64_tr_b16 v[222:223], v159 offset:25344
	ds_read_b64_tr_b16 v[224:225], v159 offset:18464
	ds_read_b64_tr_b16 v[226:227], v159 offset:20768
	ds_read_b64_tr_b16 v[228:229], v159 offset:23072
	ds_read_b64_tr_b16 v[230:231], v159 offset:25376
	ds_read_b64_tr_b16 v[232:233], v159 offset:18496
	ds_read_b64_tr_b16 v[234:235], v159 offset:20800
	ds_read_b64_tr_b16 v[236:237], v159 offset:23104
	ds_read_b64_tr_b16 v[238:239], v159 offset:25408
	ds_read_b64_tr_b16 v[240:241], v159 offset:18528
	ds_read_b64_tr_b16 v[242:243], v159 offset:20832
	ds_read_b64_tr_b16 v[244:245], v159 offset:23136
	ds_read_b64_tr_b16 v[246:247], v159 offset:25440
	s_waitcnt lgkmcnt(15)
; DI float grp16_sum(float v) { v += __shfl_xor(v, 1); v += __shfl_xor(v, 2); v += __shfl_xor(v, 4); v += __shfl_xor(v, 8); return v; }
; DI float grp16_max(float v) { v = fmaxf(v, __shfl_xor(v, 1)); v = fmaxf(v, __shfl_xor(v, 2)); v = fmaxf(v, __shfl_xor(v, 4)); v = fmaxf(v, __shfl_xor(v, 8)); return v; }
; template <int NKB>
; DI void attn_unit(const Params& p, int l, int mode, int grp, int head, int r0, int dil, int i0, int sub_len, int W, h16* lds) {
;     ...
;     mm64(Qi, Ki, S, w, lane);
;     float mx[4], al[4], rsum[4];
;     bool vm[4][4];
; #pragma unroll
;     for (int rg = 0; rg < 4; ++rg) {
;       const int row = 16 * w + 4 * q + rg;
;       float m_ = -1e30f;
; #pragma unroll
;       for (int nt = 0; nt < 4; ++nt) {
;         const int key = 16 * nt + r;
;         const int delta = row - key + W - 64 * kb;
;         const bool ok = inr && (delta >= -W) && (delta <= W);
;         vm[nt][rg] = ok;
;         float s = S[nt][rg] * 0.125f;
;         S[nt][rg] = s;
;         if (ok) m_ = fmaxf(m_, s);
;       }
;       mx[rg] = grp16_max(m_);
;     }
; #pragma unroll
;     for (int rg = 0; rg < 4; ++rg) {
;       const float mn = fmaxf(mrow[rg], mx[rg]);
;       al[rg] = __expf(mrow[rg] - mn);
;       mrow[rg] = mn;
;       float rs_ = 0.f;
; #pragma unroll
;       for (int nt = 0; nt < 4; ++nt) {
;         float pv = vm[nt][rg] ? __expf(S[nt][rg] - mn) : 0.f;
;         rs_ += pv;
;         Pi[(16 * w + 4 * q + rg) * LDH + 16 * nt + r] = (h16)pv;
;       }
;       rsum[rg] = grp16_sum(rs_);
;       lsum[rg] = lsum[rg] * al[rg] + rsum[rg];
;     }
; #pragma unroll
;     for (int et = 0; et < 4; ++et)
; #pragma unroll
;       for (int rg = 0; rg < 4; ++rg) O[et][rg] *= al[rg];
;     __syncthreads();
;     mm64(Pi, Vt, O, w, lane);
;   }
	v_mfma_f32_16x16x32_f16 v[114:117], v[18:21], v[10:13], 0
	v_mfma_f32_16x16x32_f16 v[118:121], v[26:29], v[10:13], 0
	v_mfma_f32_16x16x32_f16 v[122:125], v[34:37], v[10:13], 0
	v_mfma_f32_16x16x32_f16 v[126:129], v[42:45], v[10:13], 0
	v_mfma_f32_16x16x32_f16 v[114:117], v[22:25], v[14:17], v[114:117]
	v_mfma_f32_16x16x32_f16 v[118:121], v[30:33], v[14:17], v[118:121]
	v_mfma_f32_16x16x32_f16 v[122:125], v[38:41], v[14:17], v[122:125]
	v_mfma_f32_16x16x32_f16 v[126:129], v[46:49], v[14:17], v[126:129]
	s_nop 7
	s_nop 7
	v_mul_f32_e32 v114, 0x3e000000, v114
	v_mul_f32_e32 v115, 0x3e000000, v115
	v_mul_f32_e32 v116, 0x3e000000, v116
	v_mul_f32_e32 v117, 0x3e000000, v117
	v_mul_f32_e32 v118, 0x3e000000, v118
	v_mul_f32_e32 v119, 0x3e000000, v119
	v_mul_f32_e32 v120, 0x3e000000, v120
	v_mul_f32_e32 v121, 0x3e000000, v121
	v_mul_f32_e32 v122, 0x3e000000, v122
	v_mul_f32_e32 v123, 0x3e000000, v123
	v_mul_f32_e32 v124, 0x3e000000, v124
	v_mul_f32_e32 v125, 0x3e000000, v125
	v_mul_f32_e32 v126, 0x3e000000, v126
	v_mul_f32_e32 v127, 0x3e000000, v127
	v_mul_f32_e32 v128, 0x3e000000, v128
	v_mul_f32_e32 v129, 0x3e000000, v129
	v_max3_f32 v179, v114, v115, v116
	v_max3_f32 v179, v179, v117, v118
	v_max3_f32 v179, v179, v119, v120
	v_max3_f32 v179, v179, v121, v122
	v_max3_f32 v179, v179, v123, v124
	v_max3_f32 v179, v179, v125, v126
	v_max3_f32 v179, v179, v127, v128
	v_max_f32_e32 v179, v179, v129
	ds_bpermute_b32 v201, v174, v179
	s_waitcnt lgkmcnt(0)
	v_max_f32_e32 v179, v179, v201
	v_mov_b32_e32 v201, v179
	s_nop 1
	v_permlane32_swap_b32 v201, v179
	s_nop 1
	v_max3_f32 v179, v179, v201, v176
	v_sub_f32_e32 v178, v176, v179
	v_mul_f32_e32 v178, 0x3fb8aa3b, v178
	v_exp_f32_e32 v178, v178
	v_mov_b32_e32 v176, v179
	v_mul_f32_e32 v202, 0xbfb8aa3b, v179
	v_mov_b32_e32 v203, 0x3fb8aa3b
	v_fma_f32 v114, v114, v203, v202
	v_fma_f32 v115, v115, v203, v202
	v_fma_f32 v116, v116, v203, v202
	v_fma_f32 v117, v117, v203, v202
	v_fma_f32 v118, v118, v203, v202
	v_fma_f32 v119, v119, v203, v202
	v_fma_f32 v120, v120, v203, v202
	v_fma_f32 v121, v121, v203, v202
	v_fma_f32 v122, v122, v203, v202
	v_fma_f32 v123, v123, v203, v202
	v_fma_f32 v124, v124, v203, v202
	v_fma_f32 v125, v125, v203, v202
	v_fma_f32 v126, v126, v203, v202
	v_fma_f32 v127, v127, v203, v202
	v_fma_f32 v128, v128, v203, v202
	v_fma_f32 v129, v129, v203, v202
	v_exp_f32_e32 v114, v114
	v_exp_f32_e32 v115, v115
	v_exp_f32_e32 v116, v116
	v_exp_f32_e32 v117, v117
	v_exp_f32_e32 v118, v118
	v_exp_f32_e32 v119, v119
	v_exp_f32_e32 v120, v120
	v_exp_f32_e32 v121, v121
	v_exp_f32_e32 v122, v122
	v_exp_f32_e32 v123, v123
	v_exp_f32_e32 v124, v124
	v_exp_f32_e32 v125, v125
	v_exp_f32_e32 v126, v126
	v_exp_f32_e32 v127, v127
	v_exp_f32_e32 v128, v128
	v_exp_f32_e32 v129, v129
	s_nop 0
	v_fma_f32 v177, v177, v178, v114
	v_add_f32_e32 v177, v177, v115
	v_add_f32_e32 v177, v177, v116
	v_add_f32_e32 v177, v177, v117
	v_add_f32_e32 v177, v177, v118
	v_add_f32_e32 v177, v177, v119
	v_add_f32_e32 v177, v177, v120
	v_add_f32_e32 v177, v177, v121
	v_add_f32_e32 v177, v177, v122
	v_add_f32_e32 v177, v177, v123
	v_add_f32_e32 v177, v177, v124
	v_add_f32_e32 v177, v177, v125
	v_add_f32_e32 v177, v177, v126
	v_add_f32_e32 v177, v177, v127
	v_add_f32_e32 v177, v177, v128
	v_add_f32_e32 v177, v177, v129
	v_cvt_pk_f16_f32 v130, v114, v115
	v_cvt_pk_f16_f32 v131, v116, v117
	v_cvt_pk_f16_f32 v132, v118, v119
	v_cvt_pk_f16_f32 v133, v120, v121
	v_cvt_pk_f16_f32 v134, v122, v123
	v_cvt_pk_f16_f32 v135, v124, v125
	v_cvt_pk_f16_f32 v136, v126, v127
	v_cvt_pk_f16_f32 v137, v128, v129
	v_pk_mul_f32 v[138:139], v[138:139], v[178:179] op_sel_hi:[1,0]
	v_pk_mul_f32 v[140:141], v[140:141], v[178:179] op_sel_hi:[1,0]
	v_pk_mul_f32 v[142:143], v[142:143], v[178:179] op_sel_hi:[1,0]
	v_pk_mul_f32 v[144:145], v[144:145], v[178:179] op_sel_hi:[1,0]
	v_pk_mul_f32 v[146:147], v[146:147], v[178:179] op_sel_hi:[1,0]
	v_pk_mul_f32 v[148:149], v[148:149], v[178:179] op_sel_hi:[1,0]
	v_pk_mul_f32 v[150:151], v[150:151], v[178:179] op_sel_hi:[1,0]
	v_pk_mul_f32 v[152:153], v[152:153], v[178:179] op_sel_hi:[1,0]
	s_nop 1
	v_mfma_f32_16x16x32_f16 v[138:141], v[216:219], v[130:133], v[138:141]
	v_mfma_f32_16x16x32_f16 v[142:145], v[224:227], v[130:133], v[142:145]
	v_mfma_f32_16x16x32_f16 v[146:149], v[232:235], v[130:133], v[146:149]
	v_mfma_f32_16x16x32_f16 v[150:153], v[240:243], v[130:133], v[150:153]
	v_mfma_f32_16x16x32_f16 v[138:141], v[220:223], v[134:137], v[138:141]
	v_mfma_f32_16x16x32_f16 v[142:145], v[228:231], v[134:137], v[142:145]
	v_mfma_f32_16x16x32_f16 v[146:149], v[236:239], v[134:137], v[146:149]
	v_mfma_f32_16x16x32_f16 v[150:153], v[244:247], v[134:137], v[150:153]
; DI float grp16_sum(float v) { v += __shfl_xor(v, 1); v += __shfl_xor(v, 2); v += __shfl_xor(v, 4); v += __shfl_xor(v, 8); return v; }
; DI float grp16_max(float v) { v = fmaxf(v, __shfl_xor(v, 1)); v = fmaxf(v, __shfl_xor(v, 2)); v = fmaxf(v, __shfl_xor(v, 4)); v = fmaxf(v, __shfl_xor(v, 8)); return v; }
; template <int NKB>
; DI void attn_unit(const Params& p, int l, int mode, int grp, int head, int r0, int dil, int i0, int sub_len, int W, h16* lds) {
;     ...
;   ATT_PREFETCH(0);
;   for (int kb = 0; kb < NKB; ++kb) {
;     const int j0 = i0 - W + 64 * kb;
;     const bool inr = (j0 >= 0) && (j0 < sub_len);
;     __syncthreads();
;     img_store_nat(Ki, lrow, seg, pk0, pk1);
;     img_store_T(Vt, lrow, seg, pv0, pv1);
;     __syncthreads();
;     if (kb + 1 < NKB) ATT_PREFETCH(kb + 1);
;     f4v S[4];
; #pragma unroll
;     for (int i = 0; i < 4; ++i) S[i] = (f4v){0.f, 0.f, 0.f, 0.f};
;     mm64(Qi, Ki, S, w, lane);
;     float mx[4], al[4], rsum[4];
;     bool vm[4][4];
; #pragma unroll
;     for (int rg = 0; rg < 4; ++rg) {
;       const int row = 16 * w + 4 * q + rg;
;       float m_ = -1e30f;
; #pragma unroll
;       for (int nt = 0; nt < 4; ++nt) {
;         const int key = 16 * nt + r;
;         const int delta = row - key + W - 64 * kb;
;         const bool ok = inr && (delta >= -W) && (delta <= W);
;         vm[nt][rg] = ok;
;         float s = S[nt][rg] * 0.125f;
;         S[nt][rg] = s;
;         if (ok) m_ = fmaxf(m_, s);
;       }
;       mx[rg] = grp16_max(m_);
;     }
; #pragma unroll
;     for (int rg = 0; rg < 4; ++rg) {
;       const float mn = fmaxf(mrow[rg], mx[rg]);
;       al[rg] = __expf(mrow[rg] - mn);
;       mrow[rg] = mn;
;       float rs_ = 0.f;
; #pragma unroll
;       for (int nt = 0; nt < 4; ++nt) {
;         float pv = vm[nt][rg] ? __expf(S[nt][rg] - mn) : 0.f;
;         rs_ += pv;
;         Pi[(16 * w + 4 * q + rg) * LDH + 16 * nt + r] = (h16)pv;
;       }
;       rsum[rg] = grp16_sum(rs_);
;       lsum[rg] = lsum[rg] * al[rg] + rsum[rg];
;     }
; #pragma unroll
;     for (int et = 0; et < 4; ++et)
; #pragma unroll
;       for (int rg = 0; rg < 4; ++rg) O[et][rg] *= al[rg];
;     __syncthreads();
;     mm64(Pi, Vt, O, w, lane);
;   }
.Lat1_kb1_end:
	s_waitcnt vmcnt(4)
	ds_write_b128 v158, v[50:53] offset:36864
	ds_write_b128 v158, v[54:57] offset:38016
	ds_write_b128 v158, v[58:61] offset:46080
	ds_write_b128 v158, v[62:65] offset:47232
	s_waitcnt lgkmcnt(0)
	s_barrier
	s_add_u32 s50, s38, 128
	s_cmp_ge_i32 s50, 0
	s_cselect_b32 s56, 1, 0
	s_cmp_lt_i32 s50, s41
	s_cselect_b32 s57, 1, 0
	s_and_b32 s6, s56, s57
	s_cmp_eq_u32 s6, 1
	s_cselect_b32 s50, s50, s38
	s_mul_i32 s50, s50, s60
	s_add_u32 s50, s50, s40
	s_mul_i32 s50, s50, 0x2800
	s_add_u32 s56, s50, s54
	s_add_u32 s44, s0, s56
	s_addc_u32 s45, s1, 0
	s_add_u32 s56, s50, s55
	s_add_u32 s46, s0, s56
	s_addc_u32 s47, s1, 0
	global_load_dwordx4 v[50:53], v6, s[44:45]
	global_load_dwordx4 v[54:57], v7, s[44:45]
	global_load_dwordx4 v[58:61], v6, s[46:47]
	global_load_dwordx4 v[62:65], v7, s[46:47]
	s_cmp_eq_u32 s4, 1
	s_cbranch_scc0 .Lat1_kb2_end
	ds_read_b128 v[18:21], v8 offset:36864
	ds_read_b128 v[22:25], v8 offset:36928
	ds_read_b128 v[26:29], v8 offset:39168
	ds_read_b128 v[30:33], v8 offset:39232
	ds_read_b128 v[34:37], v8 offset:41472
	ds_read_b128 v[38:41], v8 offset:41536
	ds_read_b128 v[42:45], v8 offset:43776
	ds_read_b128 v[46:49], v8 offset:43840
	ds_read_b64_tr_b16 v[216:217], v159 offset:36864
	ds_read_b64_tr_b16 v[218:219], v159 offset:39168
	ds_read_b64_tr_b16 v[220:221], v159 offset:41472
	ds_read_b64_tr_b16 v[222:223], v159 offset:43776
	ds_read_b64_tr_b16 v[224:225], v159 offset:36896
	ds_read_b64_tr_b16 v[226:227], v159 offset:39200
	ds_read_b64_tr_b16 v[228:229], v159 offset:41504
	ds_read_b64_tr_b16 v[230:231], v159 offset:43808
	ds_read_b64_tr_b16 v[232:233], v159 offset:36928
	ds_read_b64_tr_b16 v[234:235], v159 offset:39232
	ds_read_b64_tr_b16 v[236:237], v159 offset:41536
	ds_read_b64_tr_b16 v[238:239], v159 offset:43840
	ds_read_b64_tr_b16 v[240:241], v159 offset:36960
	ds_read_b64_tr_b16 v[242:243], v159 offset:39264
	ds_read_b64_tr_b16 v[244:245], v159 offset:41568
	ds_read_b64_tr_b16 v[246:247], v159 offset:43872
	s_waitcnt lgkmcnt(15)
	v_mfma_f32_16x16x32_f16 v[114:117], v[18:21], v[10:13], 0
	v_mfma_f32_16x16x32_f16 v[118:121], v[26:29], v[10:13], 0
	v_mfma_f32_16x16x32_f16 v[122:125], v[34:37], v[10:13], 0
	v_mfma_f32_16x16x32_f16 v[126:129], v[42:45], v[10:13], 0
	v_mfma_f32_16x16x32_f16 v[114:117], v[22:25], v[14:17], v[114:117]
	v_mfma_f32_16x16x32_f16 v[118:121], v[30:33], v[14:17], v[118:121]
	v_mfma_f32_16x16x32_f16 v[122:125], v[38:41], v[14:17], v[122:125]
	v_mfma_f32_16x16x32_f16 v[126:129], v[46:49], v[14:17], v[126:129]
	s_nop 7
	s_nop 7
	v_mul_f32_e32 v114, 0x3e000000, v114
	v_mul_f32_e32 v115, 0x3e000000, v115
	v_mul_f32_e32 v116, 0x3e000000, v116
	v_mul_f32_e32 v117, 0x3e000000, v117
	v_mul_f32_e32 v118, 0x3e000000, v118
	v_mul_f32_e32 v119, 0x3e000000, v119
	v_mul_f32_e32 v120, 0x3e000000, v120
	v_mul_f32_e32 v121, 0x3e000000, v121
	v_mul_f32_e32 v122, 0x3e000000, v122
	v_mul_f32_e32 v123, 0x3e000000, v123
	v_mul_f32_e32 v124, 0x3e000000, v124
	v_mul_f32_e32 v125, 0x3e000000, v125
	v_mul_f32_e32 v126, 0x3e000000, v126
	v_mul_f32_e32 v127, 0x3e000000, v127
	v_mul_f32_e32 v128, 0x3e000000, v128
	v_mul_f32_e32 v129, 0x3e000000, v129
	v_max3_f32 v179, v114, v115, v116
	v_max3_f32 v179, v179, v117, v118
	v_max3_f32 v179, v179, v119, v120
	v_max3_f32 v179, v179, v121, v122
	v_max3_f32 v179, v179, v123, v124
	v_max3_f32 v179, v179, v125, v126
	v_max3_f32 v179, v179, v127, v128
	v_max_f32_e32 v179, v179, v129
	ds_bpermute_b32 v201, v174, v179
	s_waitcnt lgkmcnt(0)
	v_max_f32_e32 v179, v179, v201
	v_mov_b32_e32 v201, v179
	s_nop 1
	v_permlane32_swap_b32 v201, v179
	s_nop 1
	v_max3_f32 v179, v179, v201, v176
	v_sub_f32_e32 v178, v176, v179
	v_mul_f32_e32 v178, 0x3fb8aa3b, v178
	v_exp_f32_e32 v178, v178
	v_mov_b32_e32 v176, v179
	v_mul_f32_e32 v202, 0xbfb8aa3b, v179
	v_mov_b32_e32 v203, 0x3fb8aa3b
	v_fma_f32 v114, v114, v203, v202
	v_fma_f32 v115, v115, v203, v202
	v_fma_f32 v116, v116, v203, v202
	v_fma_f32 v117, v117, v203, v202
	v_fma_f32 v118, v118, v203, v202
	v_fma_f32 v119, v119, v203, v202
	v_fma_f32 v120, v120, v203, v202
	v_fma_f32 v121, v121, v203, v202
	v_fma_f32 v122, v122, v203, v202
	v_fma_f32 v123, v123, v203, v202
	v_fma_f32 v124, v124, v203, v202
	v_fma_f32 v125, v125, v203, v202
	v_fma_f32 v126, v126, v203, v202
	v_fma_f32 v127, v127, v203, v202
	v_fma_f32 v128, v128, v203, v202
	v_fma_f32 v129, v129, v203, v202
	v_exp_f32_e32 v114, v114
	v_exp_f32_e32 v115, v115
	v_exp_f32_e32 v116, v116
	v_exp_f32_e32 v117, v117
	v_exp_f32_e32 v118, v118
	v_exp_f32_e32 v119, v119
	v_exp_f32_e32 v120, v120
	v_exp_f32_e32 v121, v121
	v_exp_f32_e32 v122, v122
	v_exp_f32_e32 v123, v123
	v_exp_f32_e32 v124, v124
	v_exp_f32_e32 v125, v125
	v_exp_f32_e32 v126, v126
	v_exp_f32_e32 v127, v127
	v_exp_f32_e32 v128, v128
	v_exp_f32_e32 v129, v129
	s_nop 0
	v_fma_f32 v177, v177, v178, v114
	v_add_f32_e32 v177, v177, v115
	v_add_f32_e32 v177, v177, v116
	v_add_f32_e32 v177, v177, v117
	v_add_f32_e32 v177, v177, v118
	v_add_f32_e32 v177, v177, v119
	v_add_f32_e32 v177, v177, v120
	v_add_f32_e32 v177, v177, v121
	v_add_f32_e32 v177, v177, v122
	v_add_f32_e32 v177, v177, v123
	v_add_f32_e32 v177, v177, v124
	v_add_f32_e32 v177, v177, v125
	v_add_f32_e32 v177, v177, v126
	v_add_f32_e32 v177, v177, v127
	v_add_f32_e32 v177, v177, v128
	v_add_f32_e32 v177, v177, v129
	v_cvt_pk_f16_f32 v130, v114, v115
	v_cvt_pk_f16_f32 v131, v116, v117
	v_cvt_pk_f16_f32 v132, v118, v119
	v_cvt_pk_f16_f32 v133, v120, v121
	v_cvt_pk_f16_f32 v134, v122, v123
	v_cvt_pk_f16_f32 v135, v124, v125
	v_cvt_pk_f16_f32 v136, v126, v127
	v_cvt_pk_f16_f32 v137, v128, v129
	v_pk_mul_f32 v[138:139], v[138:139], v[178:179] op_sel_hi:[1,0]
	v_pk_mul_f32 v[140:141], v[140:141], v[178:179] op_sel_hi:[1,0]
	v_pk_mul_f32 v[142:143], v[142:143], v[178:179] op_sel_hi:[1,0]
	v_pk_mul_f32 v[144:145], v[144:145], v[178:179] op_sel_hi:[1,0]
	v_pk_mul_f32 v[146:147], v[146:147], v[178:179] op_sel_hi:[1,0]
	v_pk_mul_f32 v[148:149], v[148:149], v[178:179] op_sel_hi:[1,0]
	v_pk_mul_f32 v[150:151], v[150:151], v[178:179] op_sel_hi:[1,0]
	v_pk_mul_f32 v[152:153], v[152:153], v[178:179] op_sel_hi:[1,0]
	s_nop 1
	v_mfma_f32_16x16x32_f16 v[138:141], v[216:219], v[130:133], v[138:141]
	v_mfma_f32_16x16x32_f16 v[142:145], v[224:227], v[130:133], v[142:145]
	v_mfma_f32_16x16x32_f16 v[146:149], v[232:235], v[130:133], v[146:149]
	v_mfma_f32_16x16x32_f16 v[150:153], v[240:243], v[130:133], v[150:153]
	v_mfma_f32_16x16x32_f16 v[138:141], v[220:223], v[134:137], v[138:141]
	v_mfma_f32_16x16x32_f16 v[142:145], v[228:231], v[134:137], v[142:145]
	v_mfma_f32_16x16x32_f16 v[146:149], v[236:239], v[134:137], v[146:149]
	v_mfma_f32_16x16x32_f16 v[150:153], v[244:247], v[134:137], v[150:153]
; DI float grp16_sum(float v) { v += __shfl_xor(v, 1); v += __shfl_xor(v, 2); v += __shfl_xor(v, 4); v += __shfl_xor(v, 8); return v; }
; DI float grp16_max(float v) { v = fmaxf(v, __shfl_xor(v, 1)); v = fmaxf(v, __shfl_xor(v, 2)); v = fmaxf(v, __shfl_xor(v, 4)); v = fmaxf(v, __shfl_xor(v, 8)); return v; }
; template <int NKB>
; DI void attn_unit(const Params& p, int l, int mode, int grp, int head, int r0, int dil, int i0, int sub_len, int W, h16* lds) {
;     ...
;   for (int kb = 0; kb < NKB; ++kb) {
;     const int j0 = i0 - W + 64 * kb;
;     const bool inr = (j0 >= 0) && (j0 < sub_len);
;     __syncthreads();
;     img_store_nat(Ki, lrow, seg, pk0, pk1);
;     img_store_T(Vt, lrow, seg, pv0, pv1);
;     __syncthreads();
;     if (kb + 1 < NKB) ATT_PREFETCH(kb + 1);
;     f4v S[4];
; #pragma unroll
;     for (int i = 0; i < 4; ++i) S[i] = (f4v){0.f, 0.f, 0.f, 0.f};
;     mm64(Qi, Ki, S, w, lane);
;     float mx[4], al[4], rsum[4];
;     bool vm[4][4];
; #pragma unroll
;     for (int rg = 0; rg < 4; ++rg) {
;       const int row = 16 * w + 4 * q + rg;
;       float m_ = -1e30f;
; #pragma unroll
;       for (int nt = 0; nt < 4; ++nt) {
;         const int key = 16 * nt + r;
;         const int delta = row - key + W - 64 * kb;
;         const bool ok = inr && (delta >= -W) && (delta <= W);
;         vm[nt][rg] = ok;
;         float s = S[nt][rg] * 0.125f;
;         S[nt][rg] = s;
;         if (ok) m_ = fmaxf(m_, s);
;       }
;       mx[rg] = grp16_max(m_);
;     }
; #pragma unroll
;     for (int rg = 0; rg < 4; ++rg) {
;       const float mn = fmaxf(mrow[rg], mx[rg]);
;       al[rg] = __expf(mrow[rg] - mn);
;       mrow[rg] = mn;
;       float rs_ = 0.f;
; #pragma unroll
;       for (int nt = 0; nt < 4; ++nt) {
;         float pv = vm[nt][rg] ? __expf(S[nt][rg] - mn) : 0.f;
;         rs_ += pv;
;         Pi[(16 * w + 4 * q + rg) * LDH + 16 * nt + r] = (h16)pv;
;       }
;       rsum[rg] = grp16_sum(rs_);
;       lsum[rg] = lsum[rg] * al[rg] + rsum[rg];
;     }
; #pragma unroll
;     for (int et = 0; et < 4; ++et)
; #pragma unroll
;       for (int rg = 0; rg < 4; ++rg) O[et][rg] *= al[rg];
;     __syncthreads();
;     mm64(Pi, Vt, O, w, lane);
;   }
.Lat1_kb2_end:
	s_waitcnt vmcnt(4)
	ds_write_b128 v158, v[66:69] offset:0
	ds_write_b128 v158, v[70:73] offset:1152
	ds_write_b128 v158, v[74:77] offset:9216
	ds_write_b128 v158, v[78:81] offset:10368
	s_waitcnt lgkmcnt(0)
	s_barrier
	s_cmp_eq_u32 s5, 1
	s_cbranch_scc0 .Lat1_kb3_end
	ds_read_b128 v[18:21], v8 offset:0
	ds_read_b128 v[22:25], v8 offset:64
	ds_read_b128 v[26:29], v8 offset:2304
	ds_read_b128 v[30:33], v8 offset:2368
	ds_read_b128 v[34:37], v8 offset:4608
	ds_read_b128 v[38:41], v8 offset:4672
	ds_read_b128 v[42:45], v8 offset:6912
	ds_read_b128 v[46:49], v8 offset:6976
	ds_read_b64_tr_b16 v[216:217], v159
	ds_read_b64_tr_b16 v[218:219], v159 offset:2304
	ds_read_b64_tr_b16 v[220:221], v159 offset:4608
	ds_read_b64_tr_b16 v[222:223], v159 offset:6912
	ds_read_b64_tr_b16 v[224:225], v159 offset:32
	ds_read_b64_tr_b16 v[226:227], v159 offset:2336
	ds_read_b64_tr_b16 v[228:229], v159 offset:4640
	ds_read_b64_tr_b16 v[230:231], v159 offset:6944
	ds_read_b64_tr_b16 v[232:233], v159 offset:64
	ds_read_b64_tr_b16 v[234:235], v159 offset:2368
	ds_read_b64_tr_b16 v[236:237], v159 offset:4672
	ds_read_b64_tr_b16 v[238:239], v159 offset:6976
	ds_read_b64_tr_b16 v[240:241], v159 offset:96
	ds_read_b64_tr_b16 v[242:243], v159 offset:2400
	ds_read_b64_tr_b16 v[244:245], v159 offset:4704
	ds_read_b64_tr_b16 v[246:247], v159 offset:7008
	s_waitcnt lgkmcnt(15)
	v_mfma_f32_16x16x32_f16 v[114:117], v[18:21], v[10:13], 0
	v_mfma_f32_16x16x32_f16 v[118:121], v[26:29], v[10:13], 0
	v_mfma_f32_16x16x32_f16 v[122:125], v[34:37], v[10:13], 0
	v_mfma_f32_16x16x32_f16 v[126:129], v[42:45], v[10:13], 0
	v_mfma_f32_16x16x32_f16 v[114:117], v[22:25], v[14:17], v[114:117]
	v_mfma_f32_16x16x32_f16 v[118:121], v[30:33], v[14:17], v[118:121]
	v_mfma_f32_16x16x32_f16 v[122:125], v[38:41], v[14:17], v[122:125]
	v_mfma_f32_16x16x32_f16 v[126:129], v[46:49], v[14:17], v[126:129]
	s_nop 7
	s_nop 7
	v_mul_f32_e32 v114, 0x3e000000, v114
	v_mul_f32_e32 v115, 0x3e000000, v115
	v_mul_f32_e32 v116, 0x3e000000, v116
	v_mul_f32_e32 v117, 0x3e000000, v117
	v_mul_f32_e32 v118, 0x3e000000, v118
	v_mul_f32_e32 v119, 0x3e000000, v119
	v_mul_f32_e32 v120, 0x3e000000, v120
	v_mul_f32_e32 v121, 0x3e000000, v121
	v_mul_f32_e32 v122, 0x3e000000, v122
	v_mul_f32_e32 v123, 0x3e000000, v123
	v_mul_f32_e32 v124, 0x3e000000, v124
	v_mul_f32_e32 v125, 0x3e000000, v125
	v_mul_f32_e32 v126, 0x3e000000, v126
	v_mul_f32_e32 v127, 0x3e000000, v127
	v_mul_f32_e32 v128, 0x3e000000, v128
	v_mul_f32_e32 v129, 0x3e000000, v129
	v_max3_f32 v179, v114, v115, v116
	v_max3_f32 v179, v179, v117, v118
	v_max3_f32 v179, v179, v119, v120
	v_max3_f32 v179, v179, v121, v122
	v_max3_f32 v179, v179, v123, v124
	v_max3_f32 v179, v179, v125, v126
	v_max3_f32 v179, v179, v127, v128
	v_max_f32_e32 v179, v179, v129
	ds_bpermute_b32 v201, v174, v179
	s_waitcnt lgkmcnt(0)
	v_max_f32_e32 v179, v179, v201
	v_mov_b32_e32 v201, v179
	s_nop 1
	v_permlane32_swap_b32 v201, v179
	s_nop 1
	v_max3_f32 v179, v179, v201, v176
	v_sub_f32_e32 v178, v176, v179
	v_mul_f32_e32 v178, 0x3fb8aa3b, v178
	v_exp_f32_e32 v178, v178
	v_mov_b32_e32 v176, v179
	v_mul_f32_e32 v202, 0xbfb8aa3b, v179
	v_mov_b32_e32 v203, 0x3fb8aa3b
	v_fma_f32 v114, v114, v203, v202
	v_fma_f32 v115, v115, v203, v202
	v_fma_f32 v116, v116, v203, v202
	v_fma_f32 v117, v117, v203, v202
	v_fma_f32 v118, v118, v203, v202
	v_fma_f32 v119, v119, v203, v202
	v_fma_f32 v120, v120, v203, v202
	v_fma_f32 v121, v121, v203, v202
	v_fma_f32 v122, v122, v203, v202
	v_fma_f32 v123, v123, v203, v202
	v_fma_f32 v124, v124, v203, v202
	v_fma_f32 v125, v125, v203, v202
	v_fma_f32 v126, v126, v203, v202
	v_fma_f32 v127, v127, v203, v202
	v_fma_f32 v128, v128, v203, v202
	v_fma_f32 v129, v129, v203, v202
	v_exp_f32_e32 v114, v114
	v_exp_f32_e32 v115, v115
	v_exp_f32_e32 v116, v116
	v_exp_f32_e32 v117, v117
	v_exp_f32_e32 v118, v118
	v_exp_f32_e32 v119, v119
	v_exp_f32_e32 v120, v120
	v_exp_f32_e32 v121, v121
	v_exp_f32_e32 v122, v122
	v_exp_f32_e32 v123, v123
	v_exp_f32_e32 v124, v124
	v_exp_f32_e32 v125, v125
	v_exp_f32_e32 v126, v126
	v_exp_f32_e32 v127, v127
	v_exp_f32_e32 v128, v128
	v_exp_f32_e32 v129, v129
	s_nop 0
	v_fma_f32 v177, v177, v178, v114
	v_add_f32_e32 v177, v177, v115
	v_add_f32_e32 v177, v177, v116
	v_add_f32_e32 v177, v177, v117
	v_add_f32_e32 v177, v177, v118
	v_add_f32_e32 v177, v177, v119
	v_add_f32_e32 v177, v177, v120
	v_add_f32_e32 v177, v177, v121
	v_add_f32_e32 v177, v177, v122
	v_add_f32_e32 v177, v177, v123
	v_add_f32_e32 v177, v177, v124
	v_add_f32_e32 v177, v177, v125
	v_add_f32_e32 v177, v177, v126
	v_add_f32_e32 v177, v177, v127
	v_add_f32_e32 v177, v177, v128
	v_add_f32_e32 v177, v177, v129
	v_cvt_pk_f16_f32 v130, v114, v115
	v_cvt_pk_f16_f32 v131, v116, v117
	v_cvt_pk_f16_f32 v132, v118, v119
	v_cvt_pk_f16_f32 v133, v120, v121
	v_cvt_pk_f16_f32 v134, v122, v123
	v_cvt_pk_f16_f32 v135, v124, v125
	v_cvt_pk_f16_f32 v136, v126, v127
	v_cvt_pk_f16_f32 v137, v128, v129
	v_pk_mul_f32 v[138:139], v[138:139], v[178:179] op_sel_hi:[1,0]
	v_pk_mul_f32 v[140:141], v[140:141], v[178:179] op_sel_hi:[1,0]
	v_pk_mul_f32 v[142:143], v[142:143], v[178:179] op_sel_hi:[1,0]
	v_pk_mul_f32 v[144:145], v[144:145], v[178:179] op_sel_hi:[1,0]
	v_pk_mul_f32 v[146:147], v[146:147], v[178:179] op_sel_hi:[1,0]
	v_pk_mul_f32 v[148:149], v[148:149], v[178:179] op_sel_hi:[1,0]
	v_pk_mul_f32 v[150:151], v[150:151], v[178:179] op_sel_hi:[1,0]
	v_pk_mul_f32 v[152:153], v[152:153], v[178:179] op_sel_hi:[1,0]
	s_nop 1
	v_mfma_f32_16x16x32_f16 v[138:141], v[216:219], v[130:133], v[138:141]
	v_mfma_f32_16x16x32_f16 v[142:145], v[224:227], v[130:133], v[142:145]
	v_mfma_f32_16x16x32_f16 v[146:149], v[232:235], v[130:133], v[146:149]
	v_mfma_f32_16x16x32_f16 v[150:153], v[240:243], v[130:133], v[150:153]
	v_mfma_f32_16x16x32_f16 v[138:141], v[220:223], v[134:137], v[138:141]
	v_mfma_f32_16x16x32_f16 v[142:145], v[228:231], v[134:137], v[142:145]
	v_mfma_f32_16x16x32_f16 v[146:149], v[236:239], v[134:137], v[146:149]
	v_mfma_f32_16x16x32_f16 v[150:153], v[244:247], v[134:137], v[150:153]
; DI float grp16_max(float v) { v = fmaxf(v, __shfl_xor(v, 1)); v = fmaxf(v, __shfl_xor(v, 2)); v = fmaxf(v, __shfl_xor(v, 4)); v = fmaxf(v, __shfl_xor(v, 8)); return v; }
; template <int NKB>
; DI void attn_unit(const Params& p, int l, int mode, int grp, int head, int r0, int dil, int i0, int sub_len, int W, h16* lds) {
;     ...
;   for (int kb = 0; kb < NKB; ++kb) {
;     const int j0 = i0 - W + 64 * kb;
;     const bool inr = (j0 >= 0) && (j0 < sub_len);
;     __syncthreads();
;     img_store_nat(Ki, lrow, seg, pk0, pk1);
;     img_store_T(Vt, lrow, seg, pv0, pv1);
;     __syncthreads();
;     if (kb + 1 < NKB) ATT_PREFETCH(kb + 1);
;     f4v S[4];
; #pragma unroll
;     for (int i = 0; i < 4; ++i) S[i] = (f4v){0.f, 0.f, 0.f, 0.f};
;     mm64(Qi, Ki, S, w, lane);
;     float mx[4], al[4], rsum[4];
;     bool vm[4][4];
; #pragma unroll
;     for (int rg = 0; rg < 4; ++rg) {
;       const int row = 16 * w + 4 * q + rg;
;       float m_ = -1e30f;
; #pragma unroll
;       for (int nt = 0; nt < 4; ++nt) {
;         const int key = 16 * nt + r;
;         const int delta = row - key + W - 64 * kb;
;         const bool ok = inr && (delta >= -W) && (delta <= W);
;         vm[nt][rg] = ok;
;         float s = S[nt][rg] * 0.125f;
;         S[nt][rg] = s;
;         if (ok) m_ = fmaxf(m_, s);
;       }
;       mx[rg] = grp16_max(m_);
.Lat1_kb3_end:
	s_waitcnt vmcnt(0)
	ds_write_b128 v158, v[50:53] offset:18432
	ds_write_b128 v158, v[54:57] offset:19584
	ds_write_b128 v158, v[58:61] offset:27648
	ds_write_b128 v158, v[62:65] offset:28800
	s_waitcnt lgkmcnt(0)
	s_barrier
	s_cmp_eq_u32 s6, 1
	s_cbranch_scc0 .Lat1_kb4_end
	ds_read_b128 v[18:21], v8 offset:18432
	ds_read_b128 v[22:25], v8 offset:18496
	ds_read_b128 v[26:29], v8 offset:20736
	ds_read_b128 v[30:33], v8 offset:20800
	ds_read_b128 v[34:37], v8 offset:23040
	ds_read_b128 v[38:41], v8 offset:23104
	ds_read_b128 v[42:45], v8 offset:25344
	ds_read_b128 v[46:49], v8 offset:25408
	ds_read_b64_tr_b16 v[216:217], v159 offset:18432
	ds_read_b64_tr_b16 v[218:219], v159 offset:20736
	ds_read_b64_tr_b16 v[220:221], v159 offset:23040
	ds_read_b64_tr_b16 v[222:223], v159 offset:25344
	ds_read_b64_tr_b16 v[224:225], v159 offset:18464
	ds_read_b64_tr_b16 v[226:227], v159 offset:20768
	ds_read_b64_tr_b16 v[228:229], v159 offset:23072
	ds_read_b64_tr_b16 v[230:231], v159 offset:25376
	ds_read_b64_tr_b16 v[232:233], v159 offset:18496
	ds_read_b64_tr_b16 v[234:235], v159 offset:20800
	ds_read_b64_tr_b16 v[236:237], v159 offset:23104
	ds_read_b64_tr_b16 v[238:239], v159 offset:25408
	ds_read_b64_tr_b16 v[240:241], v159 offset:18528
	ds_read_b64_tr_b16 v[242:243], v159 offset:20832
	ds_read_b64_tr_b16 v[244:245], v159 offset:23136
	ds_read_b64_tr_b16 v[246:247], v159 offset:25440
	s_waitcnt lgkmcnt(15)
	v_mfma_f32_16x16x32_f16 v[114:117], v[18:21], v[10:13], 0
	v_mfma_f32_16x16x32_f16 v[118:121], v[26:29], v[10:13], 0
	v_mfma_f32_16x16x32_f16 v[122:125], v[34:37], v[10:13], 0
	v_mfma_f32_16x16x32_f16 v[126:129], v[42:45], v[10:13], 0
	v_mfma_f32_16x16x32_f16 v[114:117], v[22:25], v[14:17], v[114:117]
	v_mfma_f32_16x16x32_f16 v[118:121], v[30:33], v[14:17], v[118:121]
	v_mfma_f32_16x16x32_f16 v[122:125], v[38:41], v[14:17], v[122:125]
	v_mfma_f32_16x16x32_f16 v[126:129], v[46:49], v[14:17], v[126:129]
	s_nop 7
	s_nop 7
	v_mul_f32_e32 v114, 0x3e000000, v114
	v_mul_f32_e32 v115, 0x3e000000, v115
	v_mul_f32_e32 v116, 0x3e000000, v116
	v_mul_f32_e32 v117, 0x3e000000, v117
	v_mul_f32_e32 v118, 0x3e000000, v118
	v_mul_f32_e32 v119, 0x3e000000, v119
	v_mul_f32_e32 v120, 0x3e000000, v120
	v_mul_f32_e32 v121, 0x3e000000, v121
	v_mul_f32_e32 v122, 0x3e000000, v122
	v_mul_f32_e32 v123, 0x3e000000, v123
	v_mul_f32_e32 v124, 0x3e000000, v124
	v_mul_f32_e32 v125, 0x3e000000, v125
	v_mul_f32_e32 v126, 0x3e000000, v126
	v_mul_f32_e32 v127, 0x3e000000, v127
	v_mul_f32_e32 v128, 0x3e000000, v128
	v_mul_f32_e32 v129, 0x3e000000, v129
	v_mov_b32_e32 v200, 0xf149f2ca
	v_cmp_ge_i32_e32 vcc, 0, v160
	v_cndmask_b32_e32 v114, v200, v114, vcc
	v_cmp_ge_i32_e32 vcc, -1, v160
	v_cndmask_b32_e32 v115, v200, v115, vcc
	v_cmp_ge_i32_e32 vcc, -2, v160
	v_cndmask_b32_e32 v116, v200, v116, vcc
	v_cmp_ge_i32_e32 vcc, -3, v160
	v_cndmask_b32_e32 v117, v200, v117, vcc
	v_cmp_ge_i32_e32 vcc, -16, v160
	v_cndmask_b32_e32 v118, v200, v118, vcc
	v_cmp_ge_i32_e32 vcc, -17, v160
	v_cndmask_b32_e32 v119, v200, v119, vcc
	v_cmp_ge_i32_e32 vcc, -18, v160
	v_cndmask_b32_e32 v120, v200, v120, vcc
	v_cmp_ge_i32_e32 vcc, -19, v160
	v_cndmask_b32_e32 v121, v200, v121, vcc
	v_cmp_ge_i32_e32 vcc, -32, v160
	v_cndmask_b32_e32 v122, v200, v122, vcc
	v_cmp_ge_i32_e32 vcc, -33, v160
	v_cndmask_b32_e32 v123, v200, v123, vcc
	v_cmp_ge_i32_e32 vcc, -34, v160
	v_cndmask_b32_e32 v124, v200, v124, vcc
	v_cmp_ge_i32_e32 vcc, -35, v160
	v_cndmask_b32_e32 v125, v200, v125, vcc
	v_cmp_ge_i32_e32 vcc, -48, v160
	v_cndmask_b32_e32 v126, v200, v126, vcc
	v_cmp_ge_i32_e32 vcc, -49, v160
	v_cndmask_b32_e32 v127, v200, v127, vcc
	v_cmp_ge_i32_e32 vcc, -50, v160
	v_cndmask_b32_e32 v128, v200, v128, vcc
	v_cmp_ge_i32_e32 vcc, -51, v160
	v_cndmask_b32_e32 v129, v200, v129, vcc
	v_max3_f32 v179, v114, v115, v116
	v_max3_f32 v179, v179, v117, v118
	v_max3_f32 v179, v179, v119, v120
	v_max3_f32 v179, v179, v121, v122
	v_max3_f32 v179, v179, v123, v124
	v_max3_f32 v179, v179, v125, v126
	v_max3_f32 v179, v179, v127, v128
	v_max_f32_e32 v179, v179, v129
	ds_bpermute_b32 v201, v174, v179
	s_waitcnt lgkmcnt(0)
; DI float grp16_sum(float v) { v += __shfl_xor(v, 1); v += __shfl_xor(v, 2); v += __shfl_xor(v, 4); v += __shfl_xor(v, 8); return v; }
; template <int NKB>
; DI void attn_unit(const Params& p, int l, int mode, int grp, int head, int r0, int dil, int i0, int sub_len, int W, h16* lds) {
;     ...
;     }
; #pragma unroll
;     for (int rg = 0; rg < 4; ++rg) {
;       const float mn = fmaxf(mrow[rg], mx[rg]);
;       al[rg] = __expf(mrow[rg] - mn);
;       mrow[rg] = mn;
;       float rs_ = 0.f;
; #pragma unroll
;       for (int nt = 0; nt < 4; ++nt) {
;         float pv = vm[nt][rg] ? __expf(S[nt][rg] - mn) : 0.f;
;         rs_ += pv;
;         Pi[(16 * w + 4 * q + rg) * LDH + 16 * nt + r] = (h16)pv;
;       }
;       rsum[rg] = grp16_sum(rs_);
;       lsum[rg] = lsum[rg] * al[rg] + rsum[rg];
;     }
; #pragma unroll
;     for (int et = 0; et < 4; ++et)
; #pragma unroll
;       for (int rg = 0; rg < 4; ++rg) O[et][rg] *= al[rg];
;     __syncthreads();
;     mm64(Pi, Vt, O, w, lane);
;   }
; #pragma unroll
;   for (int rg = 0; rg < 4; ++rg) {
;     const int row = 16 * w + 4 * q + rg;
;     const size_t pos = (size_t)r0 + (size_t)dil * (i0 + row);
;     const float inv = 1.f / lsum[rg];
;     if (mode == 0) {
;       h16* ob = (h16*)(ws + OFF_OB) + ((size_t)grp * SEQ + pos) * 256 + head * 64;
; #pragma unroll
;       for (int et = 0; et < 4; ++et) ob[16 * et + r] = (h16)(O[et][rg] * inv);
;       if (r == 0) {
;         float* ml = (float*)(ws + OFF_MLB) + (((size_t)grp * SEQ + pos) * 4 + head) * 2;
;         ml[0] = mrow[rg]; ml[1] = lsum[rg];
;       }
;     } else {
;       h16* y = (h16*)(ws + OFF_Y) + pos * 1280 + 768 + head * 64;
; #pragma unroll
;       for (int et = 0; et < 4; ++et) y[16 * et + r] = (h16)(O[et][rg] * inv);
	v_max_f32_e32 v179, v179, v201
	v_mov_b32_e32 v201, v179
	s_nop 1
	v_permlane32_swap_b32 v201, v179
	s_nop 1
	v_max3_f32 v179, v179, v201, v176
	v_sub_f32_e32 v178, v176, v179
	v_mul_f32_e32 v178, 0x3fb8aa3b, v178
	v_exp_f32_e32 v178, v178
	v_mov_b32_e32 v176, v179
	v_mul_f32_e32 v202, 0xbfb8aa3b, v179
	v_mov_b32_e32 v203, 0x3fb8aa3b
	v_fma_f32 v114, v114, v203, v202
	v_fma_f32 v115, v115, v203, v202
	v_fma_f32 v116, v116, v203, v202
	v_fma_f32 v117, v117, v203, v202
	v_fma_f32 v118, v118, v203, v202
	v_fma_f32 v119, v119, v203, v202
	v_fma_f32 v120, v120, v203, v202
	v_fma_f32 v121, v121, v203, v202
	v_fma_f32 v122, v122, v203, v202
	v_fma_f32 v123, v123, v203, v202
	v_fma_f32 v124, v124, v203, v202
	v_fma_f32 v125, v125, v203, v202
	v_fma_f32 v126, v126, v203, v202
	v_fma_f32 v127, v127, v203, v202
	v_fma_f32 v128, v128, v203, v202
	v_fma_f32 v129, v129, v203, v202
	v_exp_f32_e32 v114, v114
	v_exp_f32_e32 v115, v115
	v_exp_f32_e32 v116, v116
	v_exp_f32_e32 v117, v117
	v_exp_f32_e32 v118, v118
	v_exp_f32_e32 v119, v119
	v_exp_f32_e32 v120, v120
	v_exp_f32_e32 v121, v121
	v_exp_f32_e32 v122, v122
	v_exp_f32_e32 v123, v123
	v_exp_f32_e32 v124, v124
	v_exp_f32_e32 v125, v125
	v_exp_f32_e32 v126, v126
	v_exp_f32_e32 v127, v127
	v_exp_f32_e32 v128, v128
	v_exp_f32_e32 v129, v129
	s_nop 0
	v_fma_f32 v177, v177, v178, v114
	v_add_f32_e32 v177, v177, v115
	v_add_f32_e32 v177, v177, v116
	v_add_f32_e32 v177, v177, v117
	v_add_f32_e32 v177, v177, v118
	v_add_f32_e32 v177, v177, v119
	v_add_f32_e32 v177, v177, v120
	v_add_f32_e32 v177, v177, v121
	v_add_f32_e32 v177, v177, v122
	v_add_f32_e32 v177, v177, v123
	v_add_f32_e32 v177, v177, v124
	v_add_f32_e32 v177, v177, v125
	v_add_f32_e32 v177, v177, v126
	v_add_f32_e32 v177, v177, v127
	v_add_f32_e32 v177, v177, v128
	v_add_f32_e32 v177, v177, v129
	v_cvt_pk_f16_f32 v130, v114, v115
	v_cvt_pk_f16_f32 v131, v116, v117
	v_cvt_pk_f16_f32 v132, v118, v119
	v_cvt_pk_f16_f32 v133, v120, v121
	v_cvt_pk_f16_f32 v134, v122, v123
	v_cvt_pk_f16_f32 v135, v124, v125
	v_cvt_pk_f16_f32 v136, v126, v127
	v_cvt_pk_f16_f32 v137, v128, v129
	v_pk_mul_f32 v[138:139], v[138:139], v[178:179] op_sel_hi:[1,0]
	v_pk_mul_f32 v[140:141], v[140:141], v[178:179] op_sel_hi:[1,0]
	v_pk_mul_f32 v[142:143], v[142:143], v[178:179] op_sel_hi:[1,0]
	v_pk_mul_f32 v[144:145], v[144:145], v[178:179] op_sel_hi:[1,0]
	v_pk_mul_f32 v[146:147], v[146:147], v[178:179] op_sel_hi:[1,0]
	v_pk_mul_f32 v[148:149], v[148:149], v[178:179] op_sel_hi:[1,0]
	v_pk_mul_f32 v[150:151], v[150:151], v[178:179] op_sel_hi:[1,0]
	v_pk_mul_f32 v[152:153], v[152:153], v[178:179] op_sel_hi:[1,0]
	s_nop 1
	v_mfma_f32_16x16x32_f16 v[138:141], v[216:219], v[130:133], v[138:141]
	v_mfma_f32_16x16x32_f16 v[142:145], v[224:227], v[130:133], v[142:145]
	v_mfma_f32_16x16x32_f16 v[146:149], v[232:235], v[130:133], v[146:149]
	v_mfma_f32_16x16x32_f16 v[150:153], v[240:243], v[130:133], v[150:153]
	v_mfma_f32_16x16x32_f16 v[138:141], v[220:223], v[134:137], v[138:141]
	v_mfma_f32_16x16x32_f16 v[142:145], v[228:231], v[134:137], v[142:145]
	v_mfma_f32_16x16x32_f16 v[146:149], v[236:239], v[134:137], v[146:149]
	v_mfma_f32_16x16x32_f16 v[150:153], v[244:247], v[134:137], v[150:153]
.Lat1_kb4_end:
	s_nop 7
	s_nop 1
	ds_bpermute_b32 v201, v174, v177
	s_waitcnt lgkmcnt(0)
	v_add_f32_e32 v177, v177, v201
	v_mov_b32_e32 v201, v177
	s_nop 1
	v_permlane32_swap_b32 v201, v177
	s_nop 1
	v_add_f32_e32 v177, v177, v201
	v_rcp_f32_e32 v178, v177
	s_nop 0
	v_pk_mul_f32 v[138:139], v[138:139], v[178:179] op_sel_hi:[1,0]
	v_pk_mul_f32 v[140:141], v[140:141], v[178:179] op_sel_hi:[1,0]
	v_pk_mul_f32 v[142:143], v[142:143], v[178:179] op_sel_hi:[1,0]
	v_pk_mul_f32 v[144:145], v[144:145], v[178:179] op_sel_hi:[1,0]
	v_pk_mul_f32 v[146:147], v[146:147], v[178:179] op_sel_hi:[1,0]
	v_pk_mul_f32 v[148:149], v[148:149], v[178:179] op_sel_hi:[1,0]
	v_pk_mul_f32 v[150:151], v[150:151], v[178:179] op_sel_hi:[1,0]
	v_pk_mul_f32 v[152:153], v[152:153], v[178:179] op_sel_hi:[1,0]
	v_cvt_pk_f16_f32 v130, v138, v139
	v_cvt_pk_f16_f32 v131, v140, v141
	v_cvt_pk_f16_f32 v132, v142, v143
	v_cvt_pk_f16_f32 v133, v144, v145
	v_cvt_pk_f16_f32 v134, v146, v147
	v_cvt_pk_f16_f32 v135, v148, v149
	v_cvt_pk_f16_f32 v136, v150, v151
	v_cvt_pk_f16_f32 v137, v152, v153
	global_store_dwordx2 v249, v[130:131], s[48:49]
	global_store_dwordx2 v249, v[132:133], s[48:49] offset:32
	global_store_dwordx2 v249, v[134:135], s[48:49] offset:64
	global_store_dwordx2 v249, v[136:137], s[48:49] offset:96
